# on top of v2: B(.,1) stage loads of segment 2 moved to segment 3 (2/4/4/6 DMAs per segment), segment-2 wait vmcnt(6)
# baseline (speedup 1.0000x reference)
; #define PG8_STAGE(bufoff, gbase, voff) do { _Pragma("unroll") for (int _i = 0; _i < 2; ++_i) \
;         __builtin_amdgcn_global_load_lds((const unsigned*)((const char*)(gbase) + (voff)[_i]), (PG8_LAS unsigned*)(lds + (bufoff) + ldsw + _i * 8192), 16, 0, 0); } while (0)
; #define PG8_LDA(dst, b, h) do { _Pragma("unroll") for (int m = 0; m < 4; ++m) _Pragma("unroll") for (int k = 0; k < 2; ++k) dst[m][k] = *(const PG8_LAS bf16x8*)(lds + PG8_SA(b, h) + aoff + m * 2048 + k * 1024); } while (0)
; #define PG8_LDB(dst, b, h) do { _Pragma("unroll") for (int n = 0; n < 2; ++n) _Pragma("unroll") for (int k = 0; k < 2; ++k) dst[n][k] = *(const PG8_LAS bf16x8*)(lds + PG8_SB(b, h) + boff + n * 2048 + k * 1024); } while (0)
; #define PG8_MMA(ai, bj, At, Bt) do { __builtin_amdgcn_s_setprio(1); _Pragma("unroll") for (int m = 0; m < 4; ++m) _Pragma("unroll") for (int n = 0; n < 2; ++n) _Pragma("unroll") for (int k = 0; k < 2; ++k) \
;         acc[ai][bj][m][n] = __builtin_amdgcn_mfma_f32_16x16x32_bf16(Bt[n][k], At[m][k], acc[ai][bj][m][n], 0, 0, 0); __builtin_amdgcn_s_setprio(0); } while (0)
; #define PG8_WAIT_V(n) asm volatile("s_waitcnt vmcnt(" #n ")" ::: "memory")
; #define PG8_BAR __builtin_amdgcn_s_barrier()
; template <class Epi, class Sched, bool ALIGN_EPI = false, bool SP2 = false>
; __device__ __forceinline__ void gemm_phase(PG8_LAS unsigned char* lds, const Gemm g, const Sched& S, const Epi& E, const int wave_id) {
;     ...
;         for (int t = 0; t < nt; t += 2) {
;             const bool last = (t == nt - 2);
;             const char* a1 = cA + (size_t)(t + 1) * kstep;
;             const char* a2 = last ? nA : cA + (size_t)(t + 2) * kstep; const char* b2 = last ? nB : cB + (size_t)(t + 2) * kstep;
;             const char* a3 = a2 + kstep; const char* b3 = b2 + kstep;
;             if (last && has_next) S.a_ready(nxt);
;             if constexpr (SP2) {
;             PG8_LDB(B0, 0, 0); PG8_LDB(B1, 0, 1); PG8_SCHED; PG8_LDA(At, 0, 0); PG8_STAGE(PG8_SA(1, 1), a1 + hstep, voffA);
;             PG8_WAIT_V(8); PG8_WAIT_L(0); PG8_BAR; PG8_MMA(0, 0, At, B0); PG8_MMA(0, 1, At, B1); PG8_BAR; PG8_SCHED;
;             PG8_LDA(At, 0, 1); PG8_STAGE(PG8_SB(0, 0), b2, voffB); PG8_STAGE(PG8_SB(0, 1), b2 + hstep, voffB); PG8_STAGE(PG8_SA(0, 0), a2, voffA);
;             PG8_WAIT_V(8); PG8_WAIT_L(0); PG8_BAR; PG8_MMA(1, 0, At, B0); PG8_MMA(1, 1, At, B1); PG8_BAR; PG8_SCHED;
.LBB0_174:
	s_add_u32 s42, s20, 0xfff80080
	s_addc_u32 s43, s21, -1
	s_add_i32 s76, 0, 0x10000
	s_cmp_eq_u32 s75, 28
	s_cselect_b32 s45, s15, s43
	s_cselect_b32 s44, s41, s42
	s_cselect_b32 s43, s13, s74
	s_cselect_b32 s42, s72, s73
	s_add_i32 s79, 0, 0x14000
	s_add_i32 m0, s56, 0xc000
	s_nop 0
	global_load_lds_dwordx4 v138, s[20:21]
	ds_read_b128 v[142:145], v230
	ds_read_b128 v[146:149], v230 offset:1024
	ds_read_b128 v[150:153], v230 offset:2048
	ds_read_b128 v[154:157], v230 offset:3072
	ds_read_b128 v[158:161], v230 offset:16384
	ds_read_b128 v[162:165], v230 offset:17408
	ds_read_b128 v[166:169], v230 offset:18432
	ds_read_b128 v[178:181], v230 offset:19456
	s_add_i32 m0, s56, 0xe000
	s_nop 0
	global_load_lds_dwordx4 v140, s[20:21]
	ds_read_b128 v[182:185], v175
	ds_read_b128 v[186:189], v175 offset:1024
	ds_read_b128 v[190:193], v175 offset:2048
	ds_read_b128 v[206:209], v175 offset:3072
	ds_read_b128 v[210:213], v175 offset:4096
	ds_read_b128 v[214:217], v175 offset:5120
	ds_read_b128 v[226:229], v175 offset:6144
	ds_read_b128 v[234:237], v175 offset:7168
	s_waitcnt vmcnt(8)
	s_waitcnt lgkmcnt(0)
	s_barrier
	s_setprio 1
	s_waitcnt lgkmcnt(0)
	v_mfma_f32_16x16x32_bf16 v[126:129], v[142:145], v[182:185], v[126:129]
	v_mfma_f32_16x16x32_bf16 v[118:121], v[150:153], v[182:185], v[118:121]
	v_mfma_f32_16x16x32_bf16 v[110:113], v[142:145], v[190:193], v[110:113]
	v_mfma_f32_16x16x32_bf16 v[102:105], v[150:153], v[190:193], v[102:105]
	v_mfma_f32_16x16x32_bf16 v[94:97], v[142:145], v[210:213], v[94:97]
	v_mfma_f32_16x16x32_bf16 v[86:89], v[150:153], v[210:213], v[86:89]
	v_mfma_f32_16x16x32_bf16 v[78:81], v[142:145], v[226:229], v[78:81]
	v_mfma_f32_16x16x32_bf16 v[70:73], v[150:153], v[226:229], v[70:73]
	v_mfma_f32_16x16x32_bf16 v[126:129], v[146:149], v[186:189], v[126:129]
	v_mfma_f32_16x16x32_bf16 v[118:121], v[154:157], v[186:189], v[118:121]
	v_mfma_f32_16x16x32_bf16 v[110:113], v[146:149], v[206:209], v[110:113]
	v_mfma_f32_16x16x32_bf16 v[102:105], v[154:157], v[206:209], v[102:105]
	v_mfma_f32_16x16x32_bf16 v[94:97], v[146:149], v[214:217], v[94:97]
	v_mfma_f32_16x16x32_bf16 v[86:89], v[154:157], v[214:217], v[86:89]
	v_mfma_f32_16x16x32_bf16 v[78:81], v[146:149], v[234:237], v[78:81]
	v_mfma_f32_16x16x32_bf16 v[70:73], v[154:157], v[234:237], v[70:73]
	s_setprio 0
	s_setprio 1
	v_mfma_f32_16x16x32_bf16 v[122:125], v[158:161], v[182:185], v[122:125]
	v_mfma_f32_16x16x32_bf16 v[114:117], v[166:169], v[182:185], v[114:117]
	v_mfma_f32_16x16x32_bf16 v[106:109], v[158:161], v[190:193], v[106:109]
	v_mfma_f32_16x16x32_bf16 v[98:101], v[166:169], v[190:193], v[98:101]
	v_mfma_f32_16x16x32_bf16 v[90:93], v[158:161], v[210:213], v[90:93]
	v_mfma_f32_16x16x32_bf16 v[82:85], v[166:169], v[210:213], v[82:85]
	v_mfma_f32_16x16x32_bf16 v[74:77], v[158:161], v[226:229], v[74:77]
	v_mfma_f32_16x16x32_bf16 v[66:69], v[166:169], v[226:229], v[66:69]
	v_mfma_f32_16x16x32_bf16 v[122:125], v[162:165], v[186:189], v[122:125]
	v_mfma_f32_16x16x32_bf16 v[114:117], v[178:181], v[186:189], v[114:117]
	v_mfma_f32_16x16x32_bf16 v[106:109], v[162:165], v[206:209], v[106:109]
	v_mfma_f32_16x16x32_bf16 v[98:101], v[178:181], v[206:209], v[98:101]
	v_mfma_f32_16x16x32_bf16 v[90:93], v[162:165], v[214:217], v[90:93]
	v_mfma_f32_16x16x32_bf16 v[82:85], v[178:181], v[214:217], v[82:85]
	v_mfma_f32_16x16x32_bf16 v[74:77], v[162:165], v[234:237], v[74:77]
	v_mfma_f32_16x16x32_bf16 v[66:69], v[178:181], v[234:237], v[66:69]
	s_setprio 0
	s_barrier
	s_add_i32 s76, s76, s53
	s_mov_b32 m0, s76
	s_nop 0
	global_load_lds_dwordx4 v132, s[42:43]
	ds_read_b128 v[182:185], v175 offset:16384
	ds_read_b128 v[186:189], v175 offset:17408
	s_add_i32 m0, s76, 0x2000
	s_add_u32 s76, s42, 0x80000
	s_addc_u32 s77, s43, 0
	s_add_i32 s79, s79, s53
	global_load_lds_dwordx4 v136, s[42:43]
	ds_read_b128 v[190:193], v175 offset:18432
	ds_read_b128 v[206:209], v175 offset:19456
	ds_read_b128 v[210:213], v175 offset:20480
	ds_read_b128 v[214:217], v175 offset:21504
	ds_read_b128 v[226:229], v175 offset:22528
	ds_read_b128 v[234:237], v175 offset:23552
	s_mov_b32 m0, s56
	s_nop 0
	global_load_lds_dwordx4 v130, s[44:45]
	s_mov_b32 m0, s57
	s_nop 0
	global_load_lds_dwordx4 v134, s[44:45]
	s_waitcnt vmcnt(6)
	s_waitcnt lgkmcnt(0)
	s_barrier
	s_setprio 1
	s_waitcnt lgkmcnt(0)
	v_mfma_f32_16x16x32_bf16 v[62:65], v[142:145], v[182:185], v[62:65]
	v_mfma_f32_16x16x32_bf16 v[54:57], v[150:153], v[182:185], v[54:57]
	v_mfma_f32_16x16x32_bf16 v[46:49], v[142:145], v[190:193], v[46:49]
	v_mfma_f32_16x16x32_bf16 v[38:41], v[150:153], v[190:193], v[38:41]
	v_mfma_f32_16x16x32_bf16 v[30:33], v[142:145], v[210:213], v[30:33]
	v_mfma_f32_16x16x32_bf16 v[22:25], v[150:153], v[210:213], v[22:25]
	v_mfma_f32_16x16x32_bf16 v[14:17], v[142:145], v[226:229], v[14:17]
	v_mfma_f32_16x16x32_bf16 v[6:9], v[150:153], v[226:229], v[6:9]
	v_mfma_f32_16x16x32_bf16 v[62:65], v[146:149], v[186:189], v[62:65]
	v_mfma_f32_16x16x32_bf16 v[54:57], v[154:157], v[186:189], v[54:57]
	v_mfma_f32_16x16x32_bf16 v[46:49], v[146:149], v[206:209], v[46:49]
	v_mfma_f32_16x16x32_bf16 v[38:41], v[154:157], v[206:209], v[38:41]
	v_mfma_f32_16x16x32_bf16 v[30:33], v[146:149], v[214:217], v[30:33]
	v_mfma_f32_16x16x32_bf16 v[22:25], v[154:157], v[214:217], v[22:25]
	v_mfma_f32_16x16x32_bf16 v[14:17], v[146:149], v[234:237], v[14:17]
	v_mfma_f32_16x16x32_bf16 v[6:9], v[154:157], v[234:237], v[6:9]
	s_setprio 0
	s_setprio 1
	v_mfma_f32_16x16x32_bf16 v[58:61], v[158:161], v[182:185], v[58:61]
	v_mfma_f32_16x16x32_bf16 v[50:53], v[166:169], v[182:185], v[50:53]
	v_mfma_f32_16x16x32_bf16 v[42:45], v[158:161], v[190:193], v[42:45]
	v_mfma_f32_16x16x32_bf16 v[34:37], v[166:169], v[190:193], v[34:37]
	v_mfma_f32_16x16x32_bf16 v[26:29], v[158:161], v[210:213], v[26:29]
	v_mfma_f32_16x16x32_bf16 v[18:21], v[166:169], v[210:213], v[18:21]
	v_mfma_f32_16x16x32_bf16 v[10:13], v[158:161], v[226:229], v[10:13]
	v_mfma_f32_16x16x32_bf16 v[2:5], v[166:169], v[226:229], v[2:5]
	v_mfma_f32_16x16x32_bf16 v[58:61], v[162:165], v[186:189], v[58:61]
	v_mfma_f32_16x16x32_bf16 v[50:53], v[178:181], v[186:189], v[50:53]
	v_mfma_f32_16x16x32_bf16 v[42:45], v[162:165], v[206:209], v[42:45]
	v_mfma_f32_16x16x32_bf16 v[34:37], v[178:181], v[206:209], v[34:37]
	v_mfma_f32_16x16x32_bf16 v[26:29], v[162:165], v[214:217], v[26:29]
	v_mfma_f32_16x16x32_bf16 v[18:21], v[178:181], v[214:217], v[18:21]
	v_mfma_f32_16x16x32_bf16 v[10:13], v[162:165], v[234:237], v[10:13]
	v_mfma_f32_16x16x32_bf16 v[2:5], v[178:181], v[234:237], v[2:5]
	s_setprio 0
	s_barrier
; #define PG8_STAGE(bufoff, gbase, voff) do { _Pragma("unroll") for (int _i = 0; _i < 2; ++_i) \
;         __builtin_amdgcn_global_load_lds((const unsigned*)((const char*)(gbase) + (voff)[_i]), (PG8_LAS unsigned*)(lds + (bufoff) + ldsw + _i * 8192), 16, 0, 0); } while (0)
; #define PG8_LDA(dst, b, h) do { _Pragma("unroll") for (int m = 0; m < 4; ++m) _Pragma("unroll") for (int k = 0; k < 2; ++k) dst[m][k] = *(const PG8_LAS bf16x8*)(lds + PG8_SA(b, h) + aoff + m * 2048 + k * 1024); } while (0)
; #define PG8_LDB(dst, b, h) do { _Pragma("unroll") for (int n = 0; n < 2; ++n) _Pragma("unroll") for (int k = 0; k < 2; ++k) dst[n][k] = *(const PG8_LAS bf16x8*)(lds + PG8_SB(b, h) + boff + n * 2048 + k * 1024); } while (0)
; #define PG8_MMA(ai, bj, At, Bt) do { __builtin_amdgcn_s_setprio(1); _Pragma("unroll") for (int m = 0; m < 4; ++m) _Pragma("unroll") for (int n = 0; n < 2; ++n) _Pragma("unroll") for (int k = 0; k < 2; ++k) \
;         acc[ai][bj][m][n] = __builtin_amdgcn_mfma_f32_16x16x32_bf16(Bt[n][k], At[m][k], acc[ai][bj][m][n], 0, 0, 0); __builtin_amdgcn_s_setprio(0); } while (0)
; #define PG8_WAIT_V(n) asm volatile("s_waitcnt vmcnt(" #n ")" ::: "memory")
; #define PG8_WAIT_L(n) asm volatile("s_waitcnt lgkmcnt(" #n ")" ::: "memory")
; #define PG8_BAR __builtin_amdgcn_s_barrier()
; #define PG8_SCHED __builtin_amdgcn_sched_barrier(0)
; template <class Epi, class Sched, bool ALIGN_EPI = false, bool SP2 = false>
; __device__ __forceinline__ void gemm_phase(PG8_LAS unsigned char* lds, const Gemm g, const Sched& S, const Epi& E, const int wave_id) {
;     ...
;             PG8_LDB(B0, 1, 0); PG8_LDB(B1, 1, 1); PG8_SCHED; PG8_LDA(At, 1, 0); PG8_STAGE(PG8_SA(0, 1), a2 + hstep, voffA);
;             PG8_WAIT_V(8); PG8_WAIT_L(0); PG8_BAR; PG8_MMA(0, 0, At, B0); PG8_MMA(0, 1, At, B1); PG8_BAR; PG8_SCHED;
;             PG8_LDA(At, 1, 1); PG8_STAGE(PG8_SB(1, 0), b3, voffB); PG8_STAGE(PG8_SB(1, 1), b3 + hstep, voffB); PG8_STAGE(PG8_SA(1, 0), a3, voffA);
;             PG8_WAIT_V(8); PG8_WAIT_L(0); PG8_BAR; PG8_MMA(1, 0, At, B0); PG8_MMA(1, 1, At, B1); PG8_BAR; PG8_SCHED;
;     ...
;         if constexpr (ALIGN_EPI) { if (wr == 0) PG8_BAR; }
	s_mov_b32 m0, s79
	s_nop 0
	global_load_lds_dwordx4 v132, s[76:77]
	s_add_i32 m0, s79, 0x2000
	s_nop 0
	global_load_lds_dwordx4 v136, s[76:77]
	s_add_i32 s76, 0, 0x18000
	s_add_i32 s77, 0, 0x1c000
	s_add_u32 s44, s44, 0x80000
	s_addc_u32 s45, s45, 0
	s_mov_b32 m0, s64
	s_nop 0
	global_load_lds_dwordx4 v130, s[44:45]
	ds_read_b128 v[142:145], v230 offset:32768
	ds_read_b128 v[146:149], v230 offset:33792
	ds_read_b128 v[150:153], v230 offset:34816
	ds_read_b128 v[154:157], v230 offset:35840
	ds_read_b128 v[158:161], v230 offset:49152
	ds_read_b128 v[162:165], v230 offset:50176
	ds_read_b128 v[166:169], v230 offset:51200
	ds_read_b128 v[178:181], v230 offset:52224
	s_mov_b32 m0, s65
	s_nop 0
	global_load_lds_dwordx4 v134, s[44:45]
	ds_read_b128 v[182:185], v175 offset:32768
	ds_read_b128 v[186:189], v175 offset:33792
	ds_read_b128 v[190:193], v175 offset:34816
	ds_read_b128 v[206:209], v175 offset:35840
	ds_read_b128 v[210:213], v175 offset:36864
	ds_read_b128 v[214:217], v175 offset:37888
	ds_read_b128 v[226:229], v175 offset:38912
	ds_read_b128 v[234:237], v175 offset:39936
	s_waitcnt vmcnt(8)
	s_waitcnt lgkmcnt(0)
	s_barrier
	s_setprio 1
	s_waitcnt lgkmcnt(0)
	v_mfma_f32_16x16x32_bf16 v[126:129], v[142:145], v[182:185], v[126:129]
	v_mfma_f32_16x16x32_bf16 v[118:121], v[150:153], v[182:185], v[118:121]
	v_mfma_f32_16x16x32_bf16 v[110:113], v[142:145], v[190:193], v[110:113]
	v_mfma_f32_16x16x32_bf16 v[102:105], v[150:153], v[190:193], v[102:105]
	v_mfma_f32_16x16x32_bf16 v[94:97], v[142:145], v[210:213], v[94:97]
	v_mfma_f32_16x16x32_bf16 v[86:89], v[150:153], v[210:213], v[86:89]
	v_mfma_f32_16x16x32_bf16 v[78:81], v[142:145], v[226:229], v[78:81]
	v_mfma_f32_16x16x32_bf16 v[70:73], v[150:153], v[226:229], v[70:73]
	v_mfma_f32_16x16x32_bf16 v[126:129], v[146:149], v[186:189], v[126:129]
	v_mfma_f32_16x16x32_bf16 v[118:121], v[154:157], v[186:189], v[118:121]
	v_mfma_f32_16x16x32_bf16 v[110:113], v[146:149], v[206:209], v[110:113]
	v_mfma_f32_16x16x32_bf16 v[102:105], v[154:157], v[206:209], v[102:105]
	v_mfma_f32_16x16x32_bf16 v[94:97], v[146:149], v[214:217], v[94:97]
	v_mfma_f32_16x16x32_bf16 v[86:89], v[154:157], v[214:217], v[86:89]
	v_mfma_f32_16x16x32_bf16 v[78:81], v[146:149], v[234:237], v[78:81]
	v_mfma_f32_16x16x32_bf16 v[70:73], v[154:157], v[234:237], v[70:73]
	s_setprio 0
	s_setprio 1
	v_mfma_f32_16x16x32_bf16 v[122:125], v[158:161], v[182:185], v[122:125]
	v_mfma_f32_16x16x32_bf16 v[114:117], v[166:169], v[182:185], v[114:117]
	v_mfma_f32_16x16x32_bf16 v[106:109], v[158:161], v[190:193], v[106:109]
	v_mfma_f32_16x16x32_bf16 v[98:101], v[166:169], v[190:193], v[98:101]
	v_mfma_f32_16x16x32_bf16 v[90:93], v[158:161], v[210:213], v[90:93]
	v_mfma_f32_16x16x32_bf16 v[82:85], v[166:169], v[210:213], v[82:85]
	v_mfma_f32_16x16x32_bf16 v[74:77], v[158:161], v[226:229], v[74:77]
	v_mfma_f32_16x16x32_bf16 v[66:69], v[166:169], v[226:229], v[66:69]
	v_mfma_f32_16x16x32_bf16 v[122:125], v[162:165], v[186:189], v[122:125]
	v_mfma_f32_16x16x32_bf16 v[114:117], v[178:181], v[186:189], v[114:117]
	v_mfma_f32_16x16x32_bf16 v[106:109], v[162:165], v[206:209], v[106:109]
	v_mfma_f32_16x16x32_bf16 v[98:101], v[178:181], v[206:209], v[98:101]
	v_mfma_f32_16x16x32_bf16 v[90:93], v[162:165], v[214:217], v[90:93]
	v_mfma_f32_16x16x32_bf16 v[82:85], v[178:181], v[214:217], v[82:85]
	v_mfma_f32_16x16x32_bf16 v[74:77], v[162:165], v[234:237], v[74:77]
	v_mfma_f32_16x16x32_bf16 v[66:69], v[178:181], v[234:237], v[66:69]
	s_setprio 0
	s_barrier
	s_add_u32 vcc_lo, s44, 0xfff80080
	s_addc_u32 vcc_hi, s45, -1
	s_mov_b32 m0, s68
	s_nop 0
	global_load_lds_dwordx4 v130, vcc
	ds_read_b128 v[182:185], v175 offset:49152
	ds_read_b128 v[186:189], v175 offset:50176
	s_mov_b32 m0, s69
	s_add_i32 s44, s76, s53
	global_load_lds_dwordx4 v134, vcc
	ds_read_b128 v[190:193], v175 offset:51200
	ds_read_b128 v[206:209], v175 offset:52224
	s_add_u32 vcc_lo, s42, 0x80
	s_addc_u32 vcc_hi, s43, 0
	s_mov_b32 m0, s44
	s_nop 0
	global_load_lds_dwordx4 v132, vcc
	ds_read_b128 v[210:213], v175 offset:53248
	ds_read_b128 v[214:217], v175 offset:54272
	s_add_i32 m0, s44, 0x2000
	s_add_u32 s42, s42, 0x80080
	s_addc_u32 s43, s43, 0
	global_load_lds_dwordx4 v136, vcc
	ds_read_b128 v[226:229], v175 offset:55296
	ds_read_b128 v[234:237], v175 offset:56320
	s_add_i32 s44, s77, s53
	s_mov_b32 m0, s44
	s_nop 0
	global_load_lds_dwordx4 v132, s[42:43]
	s_add_i32 m0, s44, 0x2000
	s_nop 0
	global_load_lds_dwordx4 v136, s[42:43]
	s_waitcnt vmcnt(8)
	s_waitcnt lgkmcnt(0)
	s_barrier
	s_setprio 1
	s_waitcnt lgkmcnt(0)
	v_mfma_f32_16x16x32_bf16 v[62:65], v[142:145], v[182:185], v[62:65]
	v_mfma_f32_16x16x32_bf16 v[54:57], v[150:153], v[182:185], v[54:57]
	v_mfma_f32_16x16x32_bf16 v[46:49], v[142:145], v[190:193], v[46:49]
	v_mfma_f32_16x16x32_bf16 v[38:41], v[150:153], v[190:193], v[38:41]
	v_mfma_f32_16x16x32_bf16 v[30:33], v[142:145], v[210:213], v[30:33]
	v_mfma_f32_16x16x32_bf16 v[22:25], v[150:153], v[210:213], v[22:25]
	v_mfma_f32_16x16x32_bf16 v[14:17], v[142:145], v[226:229], v[14:17]
	v_mfma_f32_16x16x32_bf16 v[6:9], v[150:153], v[226:229], v[6:9]
	v_mfma_f32_16x16x32_bf16 v[62:65], v[146:149], v[186:189], v[62:65]
	v_mfma_f32_16x16x32_bf16 v[54:57], v[154:157], v[186:189], v[54:57]
	v_mfma_f32_16x16x32_bf16 v[46:49], v[146:149], v[206:209], v[46:49]
	v_mfma_f32_16x16x32_bf16 v[38:41], v[154:157], v[206:209], v[38:41]
	v_mfma_f32_16x16x32_bf16 v[30:33], v[146:149], v[214:217], v[30:33]
	v_mfma_f32_16x16x32_bf16 v[22:25], v[154:157], v[214:217], v[22:25]
	v_mfma_f32_16x16x32_bf16 v[14:17], v[146:149], v[234:237], v[14:17]
	v_mfma_f32_16x16x32_bf16 v[6:9], v[154:157], v[234:237], v[6:9]
	s_setprio 0
	s_setprio 1
	v_mfma_f32_16x16x32_bf16 v[58:61], v[158:161], v[182:185], v[58:61]
	v_mfma_f32_16x16x32_bf16 v[50:53], v[166:169], v[182:185], v[50:53]
	v_mfma_f32_16x16x32_bf16 v[42:45], v[158:161], v[190:193], v[42:45]
	v_mfma_f32_16x16x32_bf16 v[34:37], v[166:169], v[190:193], v[34:37]
	v_mfma_f32_16x16x32_bf16 v[26:29], v[158:161], v[210:213], v[26:29]
	v_mfma_f32_16x16x32_bf16 v[18:21], v[166:169], v[210:213], v[18:21]
	v_mfma_f32_16x16x32_bf16 v[10:13], v[158:161], v[226:229], v[10:13]
	v_mfma_f32_16x16x32_bf16 v[2:5], v[166:169], v[226:229], v[2:5]
	v_mfma_f32_16x16x32_bf16 v[58:61], v[162:165], v[186:189], v[58:61]
	v_mfma_f32_16x16x32_bf16 v[50:53], v[178:181], v[186:189], v[50:53]
	v_mfma_f32_16x16x32_bf16 v[42:45], v[162:165], v[206:209], v[42:45]
	v_mfma_f32_16x16x32_bf16 v[34:37], v[178:181], v[206:209], v[34:37]
	v_mfma_f32_16x16x32_bf16 v[26:29], v[162:165], v[214:217], v[26:29]
	v_mfma_f32_16x16x32_bf16 v[18:21], v[178:181], v[214:217], v[18:21]
	v_mfma_f32_16x16x32_bf16 v[10:13], v[162:165], v[234:237], v[10:13]
	v_mfma_f32_16x16x32_bf16 v[2:5], v[178:181], v[234:237], v[2:5]
	s_setprio 0
	s_barrier
	s_add_i32 s75, s75, 2
	s_add_u32 s20, s20, 0x100
	s_addc_u32 s21, s21, 0
	s_add_u32 s73, s73, 0x100
	s_addc_u32 s74, s74, 0
	s_cmp_gt_u32 s75, 29
	s_cbranch_scc0 .LBB0_174
	s_and_b64 vcc, exec, s[10:11]
	s_cbranch_vccz .LBB0_177
	s_barrier

; #define PG8_STAGE(bufoff, gbase, voff) do { _Pragma("unroll") for (int _i = 0; _i < 2; ++_i) \
;         __builtin_amdgcn_global_load_lds((const unsigned*)((const char*)(gbase) + (voff)[_i]), (PG8_LAS unsigned*)(lds + (bufoff) + ldsw + _i * 8192), 16, 0, 0); } while (0)
; #define PG8_LDA(dst, b, h) do { _Pragma("unroll") for (int m = 0; m < 4; ++m) _Pragma("unroll") for (int k = 0; k < 2; ++k) dst[m][k] = *(const PG8_LAS bf16x8*)(lds + PG8_SA(b, h) + aoff + m * 2048 + k * 1024); } while (0)
; #define PG8_LDB(dst, b, h) do { _Pragma("unroll") for (int n = 0; n < 2; ++n) _Pragma("unroll") for (int k = 0; k < 2; ++k) dst[n][k] = *(const PG8_LAS bf16x8*)(lds + PG8_SB(b, h) + boff + n * 2048 + k * 1024); } while (0)
; #define PG8_MMA(ai, bj, At, Bt) do { __builtin_amdgcn_s_setprio(1); _Pragma("unroll") for (int m = 0; m < 4; ++m) _Pragma("unroll") for (int n = 0; n < 2; ++n) _Pragma("unroll") for (int k = 0; k < 2; ++k) \
;         acc[ai][bj][m][n] = __builtin_amdgcn_mfma_f32_16x16x32_bf16(Bt[n][k], At[m][k], acc[ai][bj][m][n], 0, 0, 0); __builtin_amdgcn_s_setprio(0); } while (0)
; #define PG8_WAIT_V(n) asm volatile("s_waitcnt vmcnt(" #n ")" ::: "memory")
; #define PG8_BAR __builtin_amdgcn_s_barrier()
; template <class Epi, class Sched, bool ALIGN_EPI = false, bool SP2 = false>
; __device__ __forceinline__ void gemm_phase(PG8_LAS unsigned char* lds, const Gemm g, const Sched& S, const Epi& E, const int wave_id) {
;     ...
;         for (int t = 0; t < nt; t += 2) {
;             const bool last = (t == nt - 2);
;             const char* a1 = cA + (size_t)(t + 1) * kstep;
;             const char* a2 = last ? nA : cA + (size_t)(t + 2) * kstep; const char* b2 = last ? nB : cB + (size_t)(t + 2) * kstep;
;             const char* a3 = a2 + kstep; const char* b3 = b2 + kstep;
;             if (last && has_next) S.a_ready(nxt);
;             if constexpr (SP2) {
;             PG8_LDB(B0, 0, 0); PG8_LDB(B1, 0, 1); PG8_SCHED; PG8_LDA(At, 0, 0); PG8_STAGE(PG8_SA(1, 1), a1 + hstep, voffA);
;             PG8_WAIT_V(8); PG8_WAIT_L(0); PG8_BAR; PG8_MMA(0, 0, At, B0); PG8_MMA(0, 1, At, B1); PG8_BAR; PG8_SCHED;
;             PG8_LDA(At, 0, 1); PG8_STAGE(PG8_SB(0, 0), b2, voffB); PG8_STAGE(PG8_SB(0, 1), b2 + hstep, voffB); PG8_STAGE(PG8_SA(0, 0), a2, voffA);
;             PG8_WAIT_V(8); PG8_WAIT_L(0); PG8_BAR; PG8_MMA(1, 0, At, B0); PG8_MMA(1, 1, At, B1); PG8_BAR; PG8_SCHED;
.LBB0_524:
	s_add_u32 s42, s40, 0xfff80080
	s_addc_u32 s43, s41, -1
	s_add_i32 s77, 0, 0x10000
	s_cmp_eq_u32 s76, 28
	s_cselect_b32 s45, s15, s43
	s_cselect_b32 s44, s21, s42
	s_cselect_b32 s43, s13, s75
	s_cselect_b32 s42, s73, s74
	s_add_i32 s79, 0, 0x14000
	s_add_i32 m0, s56, 0xc000
	s_nop 0
	global_load_lds_dwordx4 v210, s[40:41]
	ds_read_b128 v[118:121], v226
	ds_read_b128 v[122:125], v226 offset:1024
	ds_read_b128 v[130:133], v226 offset:2048
	ds_read_b128 v[134:137], v226 offset:3072
	ds_read_b128 v[146:149], v226 offset:16384
	ds_read_b128 v[150:153], v226 offset:17408
	ds_read_b128 v[154:157], v226 offset:18432
	ds_read_b128 v[158:161], v226 offset:19456
	s_add_i32 m0, s56, 0xe000
	s_nop 0
	global_load_lds_dwordx4 v212, s[40:41]
	ds_read_b128 v[162:165], v222
	ds_read_b128 v[166:169], v222 offset:1024
	ds_read_b128 v[170:173], v222 offset:2048
	ds_read_b128 v[174:177], v222 offset:3072
	ds_read_b128 v[178:181], v222 offset:4096
	ds_read_b128 v[182:185], v222 offset:5120
	ds_read_b128 v[186:189], v222 offset:6144
	ds_read_b128 v[214:217], v222 offset:7168
	s_waitcnt vmcnt(8)
	s_waitcnt lgkmcnt(0)
	s_barrier
	s_setprio 1
	s_waitcnt lgkmcnt(0)
	v_mfma_f32_16x16x32_bf16 v[142:145], v[118:121], v[162:165], v[142:145]
	v_mfma_f32_16x16x32_bf16 v[138:141], v[130:133], v[162:165], v[138:141]
	v_mfma_f32_16x16x32_bf16 v[110:113], v[118:121], v[170:173], v[110:113]
	v_mfma_f32_16x16x32_bf16 v[106:109], v[130:133], v[170:173], v[106:109]
	v_mfma_f32_16x16x32_bf16 v[94:97], v[118:121], v[178:181], v[94:97]
	v_mfma_f32_16x16x32_bf16 v[90:93], v[130:133], v[178:181], v[90:93]
	v_mfma_f32_16x16x32_bf16 v[78:81], v[118:121], v[186:189], v[78:81]
	v_mfma_f32_16x16x32_bf16 v[74:77], v[130:133], v[186:189], v[74:77]
	v_mfma_f32_16x16x32_bf16 v[142:145], v[122:125], v[166:169], v[142:145]
	v_mfma_f32_16x16x32_bf16 v[138:141], v[134:137], v[166:169], v[138:141]
	v_mfma_f32_16x16x32_bf16 v[110:113], v[122:125], v[174:177], v[110:113]
	v_mfma_f32_16x16x32_bf16 v[106:109], v[134:137], v[174:177], v[106:109]
	v_mfma_f32_16x16x32_bf16 v[94:97], v[122:125], v[182:185], v[94:97]
	v_mfma_f32_16x16x32_bf16 v[90:93], v[134:137], v[182:185], v[90:93]
	v_mfma_f32_16x16x32_bf16 v[78:81], v[122:125], v[214:217], v[78:81]
	v_mfma_f32_16x16x32_bf16 v[74:77], v[134:137], v[214:217], v[74:77]
	s_setprio 0
	s_setprio 1
	v_mfma_f32_16x16x32_bf16 v[126:129], v[146:149], v[162:165], v[126:129]
	v_mfma_f32_16x16x32_bf16 v[114:117], v[154:157], v[162:165], v[114:117]
	v_mfma_f32_16x16x32_bf16 v[102:105], v[146:149], v[170:173], v[102:105]
	v_mfma_f32_16x16x32_bf16 v[98:101], v[154:157], v[170:173], v[98:101]
	v_mfma_f32_16x16x32_bf16 v[86:89], v[146:149], v[178:181], v[86:89]
	v_mfma_f32_16x16x32_bf16 v[82:85], v[154:157], v[178:181], v[82:85]
	v_mfma_f32_16x16x32_bf16 v[70:73], v[146:149], v[186:189], v[70:73]
	v_mfma_f32_16x16x32_bf16 v[66:69], v[154:157], v[186:189], v[66:69]
	v_mfma_f32_16x16x32_bf16 v[126:129], v[150:153], v[166:169], v[126:129]
	v_mfma_f32_16x16x32_bf16 v[114:117], v[158:161], v[166:169], v[114:117]
	v_mfma_f32_16x16x32_bf16 v[102:105], v[150:153], v[174:177], v[102:105]
	v_mfma_f32_16x16x32_bf16 v[98:101], v[158:161], v[174:177], v[98:101]
	v_mfma_f32_16x16x32_bf16 v[86:89], v[150:153], v[182:185], v[86:89]
	v_mfma_f32_16x16x32_bf16 v[82:85], v[158:161], v[182:185], v[82:85]
	v_mfma_f32_16x16x32_bf16 v[70:73], v[150:153], v[214:217], v[70:73]
	v_mfma_f32_16x16x32_bf16 v[66:69], v[158:161], v[214:217], v[66:69]
	s_setprio 0
	s_barrier
	s_add_i32 s77, s77, s53
	s_mov_b32 m0, s77
	s_nop 0
	global_load_lds_dwordx4 v192, s[42:43]
	ds_read_b128 v[162:165], v222 offset:16384
	ds_read_b128 v[166:169], v222 offset:17408
	s_add_i32 m0, s77, 0x2000
	s_add_u32 s80, s42, 0x80000
	s_addc_u32 s81, s43, 0
	s_add_i32 s77, s79, s53
	global_load_lds_dwordx4 v208, s[42:43]
	ds_read_b128 v[170:173], v222 offset:18432
	ds_read_b128 v[174:177], v222 offset:19456
	ds_read_b128 v[178:181], v222 offset:20480
	ds_read_b128 v[182:185], v222 offset:21504
	ds_read_b128 v[186:189], v222 offset:22528
	ds_read_b128 v[214:217], v222 offset:23552
	s_mov_b32 m0, s56
	s_nop 0
	global_load_lds_dwordx4 v190, s[44:45]
	s_mov_b32 m0, s57
	s_nop 0
	global_load_lds_dwordx4 v206, s[44:45]
	s_waitcnt vmcnt(6)
	s_waitcnt lgkmcnt(0)
	s_barrier
	s_setprio 1
	s_waitcnt lgkmcnt(0)
	v_mfma_f32_16x16x32_bf16 v[62:65], v[118:121], v[162:165], v[62:65]
	v_mfma_f32_16x16x32_bf16 v[58:61], v[130:133], v[162:165], v[58:61]
	v_mfma_f32_16x16x32_bf16 v[46:49], v[118:121], v[170:173], v[46:49]
	v_mfma_f32_16x16x32_bf16 v[42:45], v[130:133], v[170:173], v[42:45]
	v_mfma_f32_16x16x32_bf16 v[30:33], v[118:121], v[178:181], v[30:33]
	v_mfma_f32_16x16x32_bf16 v[26:29], v[130:133], v[178:181], v[26:29]
	v_mfma_f32_16x16x32_bf16 v[14:17], v[118:121], v[186:189], v[14:17]
	v_mfma_f32_16x16x32_bf16 v[10:13], v[130:133], v[186:189], v[10:13]
	v_mfma_f32_16x16x32_bf16 v[62:65], v[122:125], v[166:169], v[62:65]
	v_mfma_f32_16x16x32_bf16 v[58:61], v[134:137], v[166:169], v[58:61]
	v_mfma_f32_16x16x32_bf16 v[46:49], v[122:125], v[174:177], v[46:49]
	v_mfma_f32_16x16x32_bf16 v[42:45], v[134:137], v[174:177], v[42:45]
	v_mfma_f32_16x16x32_bf16 v[30:33], v[122:125], v[182:185], v[30:33]
	v_mfma_f32_16x16x32_bf16 v[26:29], v[134:137], v[182:185], v[26:29]
	v_mfma_f32_16x16x32_bf16 v[14:17], v[122:125], v[214:217], v[14:17]
	v_mfma_f32_16x16x32_bf16 v[10:13], v[134:137], v[214:217], v[10:13]
	s_setprio 0
	s_setprio 1
	v_mfma_f32_16x16x32_bf16 v[54:57], v[146:149], v[162:165], v[54:57]
	v_mfma_f32_16x16x32_bf16 v[50:53], v[154:157], v[162:165], v[50:53]
	v_mfma_f32_16x16x32_bf16 v[38:41], v[146:149], v[170:173], v[38:41]
	v_mfma_f32_16x16x32_bf16 v[34:37], v[154:157], v[170:173], v[34:37]
	v_mfma_f32_16x16x32_bf16 v[22:25], v[146:149], v[178:181], v[22:25]
	v_mfma_f32_16x16x32_bf16 v[18:21], v[154:157], v[178:181], v[18:21]
	v_mfma_f32_16x16x32_bf16 v[6:9], v[146:149], v[186:189], v[6:9]
	v_mfma_f32_16x16x32_bf16 v[2:5], v[154:157], v[186:189], v[2:5]
	v_mfma_f32_16x16x32_bf16 v[54:57], v[150:153], v[166:169], v[54:57]
	v_mfma_f32_16x16x32_bf16 v[50:53], v[158:161], v[166:169], v[50:53]
	v_mfma_f32_16x16x32_bf16 v[38:41], v[150:153], v[174:177], v[38:41]
	v_mfma_f32_16x16x32_bf16 v[34:37], v[158:161], v[174:177], v[34:37]
	v_mfma_f32_16x16x32_bf16 v[22:25], v[150:153], v[182:185], v[22:25]
	v_mfma_f32_16x16x32_bf16 v[18:21], v[158:161], v[182:185], v[18:21]
	v_mfma_f32_16x16x32_bf16 v[6:9], v[150:153], v[214:217], v[6:9]
	v_mfma_f32_16x16x32_bf16 v[2:5], v[158:161], v[214:217], v[2:5]
	s_setprio 0
	s_barrier
; #define PG8_STAGE(bufoff, gbase, voff) do { _Pragma("unroll") for (int _i = 0; _i < 2; ++_i) \
;         __builtin_amdgcn_global_load_lds((const unsigned*)((const char*)(gbase) + (voff)[_i]), (PG8_LAS unsigned*)(lds + (bufoff) + ldsw + _i * 8192), 16, 0, 0); } while (0)
; #define PG8_LDA(dst, b, h) do { _Pragma("unroll") for (int m = 0; m < 4; ++m) _Pragma("unroll") for (int k = 0; k < 2; ++k) dst[m][k] = *(const PG8_LAS bf16x8*)(lds + PG8_SA(b, h) + aoff + m * 2048 + k * 1024); } while (0)
; #define PG8_LDB(dst, b, h) do { _Pragma("unroll") for (int n = 0; n < 2; ++n) _Pragma("unroll") for (int k = 0; k < 2; ++k) dst[n][k] = *(const PG8_LAS bf16x8*)(lds + PG8_SB(b, h) + boff + n * 2048 + k * 1024); } while (0)
; #define PG8_MMA(ai, bj, At, Bt) do { __builtin_amdgcn_s_setprio(1); _Pragma("unroll") for (int m = 0; m < 4; ++m) _Pragma("unroll") for (int n = 0; n < 2; ++n) _Pragma("unroll") for (int k = 0; k < 2; ++k) \
;         acc[ai][bj][m][n] = __builtin_amdgcn_mfma_f32_16x16x32_bf16(Bt[n][k], At[m][k], acc[ai][bj][m][n], 0, 0, 0); __builtin_amdgcn_s_setprio(0); } while (0)
; #define PG8_WAIT_V(n) asm volatile("s_waitcnt vmcnt(" #n ")" ::: "memory")
; #define PG8_WAIT_L(n) asm volatile("s_waitcnt lgkmcnt(" #n ")" ::: "memory")
; #define PG8_BAR __builtin_amdgcn_s_barrier()
; #define PG8_SCHED __builtin_amdgcn_sched_barrier(0)
; template <class Epi, class Sched, bool ALIGN_EPI = false, bool SP2 = false>
; __device__ __forceinline__ void gemm_phase(PG8_LAS unsigned char* lds, const Gemm g, const Sched& S, const Epi& E, const int wave_id) {
;     ...
;             PG8_LDB(B0, 1, 0); PG8_LDB(B1, 1, 1); PG8_SCHED; PG8_LDA(At, 1, 0); PG8_STAGE(PG8_SA(0, 1), a2 + hstep, voffA);
;             PG8_WAIT_V(8); PG8_WAIT_L(0); PG8_BAR; PG8_MMA(0, 0, At, B0); PG8_MMA(0, 1, At, B1); PG8_BAR; PG8_SCHED;
;             PG8_LDA(At, 1, 1); PG8_STAGE(PG8_SB(1, 0), b3, voffB); PG8_STAGE(PG8_SB(1, 1), b3 + hstep, voffB); PG8_STAGE(PG8_SA(1, 0), a3, voffA);
;             PG8_WAIT_V(8); PG8_WAIT_L(0); PG8_BAR; PG8_MMA(1, 0, At, B0); PG8_MMA(1, 1, At, B1); PG8_BAR; PG8_SCHED;
;     ...
;         if constexpr (ALIGN_EPI) { if (wr == 0) PG8_BAR; }
	s_mov_b32 m0, s77
	s_nop 0
	global_load_lds_dwordx4 v192, s[80:81]
	s_add_i32 m0, s77, 0x2000
	s_nop 0
	global_load_lds_dwordx4 v208, s[80:81]
	s_add_i32 s77, 0, 0x18000
	s_add_i32 s79, 0, 0x1c000
	s_add_u32 s44, s44, 0x80000
	s_addc_u32 s45, s45, 0
	s_mov_b32 m0, s64
	s_nop 0
	global_load_lds_dwordx4 v190, s[44:45]
	ds_read_b128 v[118:121], v226 offset:32768
	ds_read_b128 v[122:125], v226 offset:33792
	ds_read_b128 v[130:133], v226 offset:34816
	ds_read_b128 v[134:137], v226 offset:35840
	ds_read_b128 v[146:149], v226 offset:49152
	ds_read_b128 v[150:153], v226 offset:50176
	ds_read_b128 v[154:157], v226 offset:51200
	ds_read_b128 v[158:161], v226 offset:52224
	s_mov_b32 m0, s65
	s_nop 0
	global_load_lds_dwordx4 v206, s[44:45]
	ds_read_b128 v[162:165], v222 offset:32768
	ds_read_b128 v[166:169], v222 offset:33792
	ds_read_b128 v[170:173], v222 offset:34816
	ds_read_b128 v[174:177], v222 offset:35840
	ds_read_b128 v[178:181], v222 offset:36864
	ds_read_b128 v[182:185], v222 offset:37888
	ds_read_b128 v[186:189], v222 offset:38912
	ds_read_b128 v[214:217], v222 offset:39936
	s_waitcnt vmcnt(8)
	s_waitcnt lgkmcnt(0)
	s_barrier
	s_setprio 1
	s_waitcnt lgkmcnt(0)
	v_mfma_f32_16x16x32_bf16 v[142:145], v[118:121], v[162:165], v[142:145]
	v_mfma_f32_16x16x32_bf16 v[138:141], v[130:133], v[162:165], v[138:141]
	v_mfma_f32_16x16x32_bf16 v[110:113], v[118:121], v[170:173], v[110:113]
	v_mfma_f32_16x16x32_bf16 v[106:109], v[130:133], v[170:173], v[106:109]
	v_mfma_f32_16x16x32_bf16 v[94:97], v[118:121], v[178:181], v[94:97]
	v_mfma_f32_16x16x32_bf16 v[90:93], v[130:133], v[178:181], v[90:93]
	v_mfma_f32_16x16x32_bf16 v[78:81], v[118:121], v[186:189], v[78:81]
	v_mfma_f32_16x16x32_bf16 v[74:77], v[130:133], v[186:189], v[74:77]
	v_mfma_f32_16x16x32_bf16 v[142:145], v[122:125], v[166:169], v[142:145]
	v_mfma_f32_16x16x32_bf16 v[138:141], v[134:137], v[166:169], v[138:141]
	v_mfma_f32_16x16x32_bf16 v[110:113], v[122:125], v[174:177], v[110:113]
	v_mfma_f32_16x16x32_bf16 v[106:109], v[134:137], v[174:177], v[106:109]
	v_mfma_f32_16x16x32_bf16 v[94:97], v[122:125], v[182:185], v[94:97]
	v_mfma_f32_16x16x32_bf16 v[90:93], v[134:137], v[182:185], v[90:93]
	v_mfma_f32_16x16x32_bf16 v[78:81], v[122:125], v[214:217], v[78:81]
	v_mfma_f32_16x16x32_bf16 v[74:77], v[134:137], v[214:217], v[74:77]
	s_setprio 0
	s_setprio 1
	v_mfma_f32_16x16x32_bf16 v[126:129], v[146:149], v[162:165], v[126:129]
	v_mfma_f32_16x16x32_bf16 v[114:117], v[154:157], v[162:165], v[114:117]
	v_mfma_f32_16x16x32_bf16 v[102:105], v[146:149], v[170:173], v[102:105]
	v_mfma_f32_16x16x32_bf16 v[98:101], v[154:157], v[170:173], v[98:101]
	v_mfma_f32_16x16x32_bf16 v[86:89], v[146:149], v[178:181], v[86:89]
	v_mfma_f32_16x16x32_bf16 v[82:85], v[154:157], v[178:181], v[82:85]
	v_mfma_f32_16x16x32_bf16 v[70:73], v[146:149], v[186:189], v[70:73]
	v_mfma_f32_16x16x32_bf16 v[66:69], v[154:157], v[186:189], v[66:69]
	v_mfma_f32_16x16x32_bf16 v[126:129], v[150:153], v[166:169], v[126:129]
	v_mfma_f32_16x16x32_bf16 v[114:117], v[158:161], v[166:169], v[114:117]
	v_mfma_f32_16x16x32_bf16 v[102:105], v[150:153], v[174:177], v[102:105]
	v_mfma_f32_16x16x32_bf16 v[98:101], v[158:161], v[174:177], v[98:101]
	v_mfma_f32_16x16x32_bf16 v[86:89], v[150:153], v[182:185], v[86:89]
	v_mfma_f32_16x16x32_bf16 v[82:85], v[158:161], v[182:185], v[82:85]
	v_mfma_f32_16x16x32_bf16 v[70:73], v[150:153], v[214:217], v[70:73]
	v_mfma_f32_16x16x32_bf16 v[66:69], v[158:161], v[214:217], v[66:69]
	s_setprio 0
	s_barrier
	s_add_u32 vcc_lo, s44, 0xfff80080
	s_addc_u32 vcc_hi, s45, -1
	s_mov_b32 m0, s70
	s_nop 0
	global_load_lds_dwordx4 v190, vcc
	ds_read_b128 v[162:165], v222 offset:49152
	ds_read_b128 v[166:169], v222 offset:50176
	s_mov_b32 m0, s71
	s_add_i32 s44, s77, s53
	global_load_lds_dwordx4 v206, vcc
	ds_read_b128 v[170:173], v222 offset:51200
	ds_read_b128 v[174:177], v222 offset:52224
	s_add_u32 vcc_lo, s42, 0x80
	s_addc_u32 vcc_hi, s43, 0
	s_mov_b32 m0, s44
	s_nop 0
	global_load_lds_dwordx4 v192, vcc
	ds_read_b128 v[178:181], v222 offset:53248
	ds_read_b128 v[182:185], v222 offset:54272
	s_add_i32 m0, s44, 0x2000
	s_add_u32 s42, s42, 0x80080
	s_addc_u32 s43, s43, 0
	global_load_lds_dwordx4 v208, vcc
	ds_read_b128 v[186:189], v222 offset:55296
	ds_read_b128 v[214:217], v222 offset:56320
	s_add_i32 s44, s79, s53
	s_mov_b32 m0, s44
	s_nop 0
	global_load_lds_dwordx4 v192, s[42:43]
	s_add_i32 m0, s44, 0x2000
	s_nop 0
	global_load_lds_dwordx4 v208, s[42:43]
	s_waitcnt vmcnt(8)
	s_waitcnt lgkmcnt(0)
	s_barrier
	s_setprio 1
	s_waitcnt lgkmcnt(0)
	v_mfma_f32_16x16x32_bf16 v[62:65], v[118:121], v[162:165], v[62:65]
	v_mfma_f32_16x16x32_bf16 v[58:61], v[130:133], v[162:165], v[58:61]
	v_mfma_f32_16x16x32_bf16 v[46:49], v[118:121], v[170:173], v[46:49]
	v_mfma_f32_16x16x32_bf16 v[42:45], v[130:133], v[170:173], v[42:45]
	v_mfma_f32_16x16x32_bf16 v[30:33], v[118:121], v[178:181], v[30:33]
	v_mfma_f32_16x16x32_bf16 v[26:29], v[130:133], v[178:181], v[26:29]
	v_mfma_f32_16x16x32_bf16 v[14:17], v[118:121], v[186:189], v[14:17]
	v_mfma_f32_16x16x32_bf16 v[10:13], v[130:133], v[186:189], v[10:13]
	v_mfma_f32_16x16x32_bf16 v[62:65], v[122:125], v[166:169], v[62:65]
	v_mfma_f32_16x16x32_bf16 v[58:61], v[134:137], v[166:169], v[58:61]
	v_mfma_f32_16x16x32_bf16 v[46:49], v[122:125], v[174:177], v[46:49]
	v_mfma_f32_16x16x32_bf16 v[42:45], v[134:137], v[174:177], v[42:45]
	v_mfma_f32_16x16x32_bf16 v[30:33], v[122:125], v[182:185], v[30:33]
	v_mfma_f32_16x16x32_bf16 v[26:29], v[134:137], v[182:185], v[26:29]
	v_mfma_f32_16x16x32_bf16 v[14:17], v[122:125], v[214:217], v[14:17]
	v_mfma_f32_16x16x32_bf16 v[10:13], v[134:137], v[214:217], v[10:13]
	s_setprio 0
	s_setprio 1
	v_mfma_f32_16x16x32_bf16 v[54:57], v[146:149], v[162:165], v[54:57]
	v_mfma_f32_16x16x32_bf16 v[50:53], v[154:157], v[162:165], v[50:53]
	v_mfma_f32_16x16x32_bf16 v[38:41], v[146:149], v[170:173], v[38:41]
	v_mfma_f32_16x16x32_bf16 v[34:37], v[154:157], v[170:173], v[34:37]
	v_mfma_f32_16x16x32_bf16 v[22:25], v[146:149], v[178:181], v[22:25]
	v_mfma_f32_16x16x32_bf16 v[18:21], v[154:157], v[178:181], v[18:21]
	v_mfma_f32_16x16x32_bf16 v[6:9], v[146:149], v[186:189], v[6:9]
	v_mfma_f32_16x16x32_bf16 v[2:5], v[154:157], v[186:189], v[2:5]
	v_mfma_f32_16x16x32_bf16 v[54:57], v[150:153], v[166:169], v[54:57]
	v_mfma_f32_16x16x32_bf16 v[50:53], v[158:161], v[166:169], v[50:53]
	v_mfma_f32_16x16x32_bf16 v[38:41], v[150:153], v[174:177], v[38:41]
	v_mfma_f32_16x16x32_bf16 v[34:37], v[158:161], v[174:177], v[34:37]
	v_mfma_f32_16x16x32_bf16 v[22:25], v[150:153], v[182:185], v[22:25]
	v_mfma_f32_16x16x32_bf16 v[18:21], v[158:161], v[182:185], v[18:21]
	v_mfma_f32_16x16x32_bf16 v[6:9], v[150:153], v[214:217], v[6:9]
	v_mfma_f32_16x16x32_bf16 v[2:5], v[158:161], v[214:217], v[2:5]
	s_setprio 0
	s_barrier
	s_add_i32 s76, s76, 2
	s_add_u32 s40, s40, 0x100
	s_addc_u32 s41, s41, 0
	s_add_u32 s74, s74, 0x100
	s_addc_u32 s75, s75, 0
	s_cmp_gt_u32 s76, 29
	s_cbranch_scc0 .LBB0_524
	s_and_b64 vcc, exec, s[10:11]
	s_cbranch_vccz .LBB0_527
	s_barrier

; #define PG8_STAGE(bufoff, gbase, voff) do { _Pragma("unroll") for (int _i = 0; _i < 2; ++_i) \
;         __builtin_amdgcn_global_load_lds((const unsigned*)((const char*)(gbase) + (voff)[_i]), (PG8_LAS unsigned*)(lds + (bufoff) + ldsw + _i * 8192), 16, 0, 0); } while (0)
; #define PG8_LDA(dst, b, h) do { _Pragma("unroll") for (int m = 0; m < 4; ++m) _Pragma("unroll") for (int k = 0; k < 2; ++k) dst[m][k] = *(const PG8_LAS bf16x8*)(lds + PG8_SA(b, h) + aoff + m * 2048 + k * 1024); } while (0)
; #define PG8_LDB(dst, b, h) do { _Pragma("unroll") for (int n = 0; n < 2; ++n) _Pragma("unroll") for (int k = 0; k < 2; ++k) dst[n][k] = *(const PG8_LAS bf16x8*)(lds + PG8_SB(b, h) + boff + n * 2048 + k * 1024); } while (0)
; #define PG8_MMA(ai, bj, At, Bt) do { __builtin_amdgcn_s_setprio(1); _Pragma("unroll") for (int m = 0; m < 4; ++m) _Pragma("unroll") for (int n = 0; n < 2; ++n) _Pragma("unroll") for (int k = 0; k < 2; ++k) \
;         acc[ai][bj][m][n] = __builtin_amdgcn_mfma_f32_16x16x32_bf16(Bt[n][k], At[m][k], acc[ai][bj][m][n], 0, 0, 0); __builtin_amdgcn_s_setprio(0); } while (0)
; #define PG8_WAIT_V(n) asm volatile("s_waitcnt vmcnt(" #n ")" ::: "memory")
; #define PG8_BAR __builtin_amdgcn_s_barrier()
; template <class Epi, class Sched, bool ALIGN_EPI = false, bool SP2 = false>
; __device__ __forceinline__ void gemm_phase(PG8_LAS unsigned char* lds, const Gemm g, const Sched& S, const Epi& E, const int wave_id) {
;     ...
;         for (int t = 0; t < nt; t += 2) {
;             const bool last = (t == nt - 2);
;             const char* a1 = cA + (size_t)(t + 1) * kstep;
;             const char* a2 = last ? nA : cA + (size_t)(t + 2) * kstep; const char* b2 = last ? nB : cB + (size_t)(t + 2) * kstep;
;             const char* a3 = a2 + kstep; const char* b3 = b2 + kstep;
;             if (last && has_next) S.a_ready(nxt);
;             if constexpr (SP2) {
;             PG8_LDB(B0, 0, 0); PG8_LDB(B1, 0, 1); PG8_SCHED; PG8_LDA(At, 0, 0); PG8_STAGE(PG8_SA(1, 1), a1 + hstep, voffA);
;             PG8_WAIT_V(8); PG8_WAIT_L(0); PG8_BAR; PG8_MMA(0, 0, At, B0); PG8_MMA(0, 1, At, B1); PG8_BAR; PG8_SCHED;
;             PG8_LDA(At, 0, 1); PG8_STAGE(PG8_SB(0, 0), b2, voffB); PG8_STAGE(PG8_SB(0, 1), b2 + hstep, voffB); PG8_STAGE(PG8_SA(0, 0), a2, voffA);
;             PG8_WAIT_V(8); PG8_WAIT_L(0); PG8_BAR; PG8_MMA(1, 0, At, B0); PG8_MMA(1, 1, At, B1); PG8_BAR; PG8_SCHED;
.LBB0_641:
	s_add_u32 s42, s20, 0xfff80080
	s_addc_u32 s43, s21, -1
	s_add_i32 s76, 0, 0x10000
	s_cmp_eq_u32 s75, 28
	s_cselect_b32 s45, s15, s43
	s_cselect_b32 s44, s71, s42
	s_cselect_b32 s43, s13, s74
	s_cselect_b32 s42, s72, s73
	s_add_i32 s79, 0, 0x14000
	s_add_i32 m0, s53, 0xc000
	s_nop 0
	global_load_lds_dwordx4 v138, s[20:21]
	ds_read_b128 v[158:161], v144
	ds_read_b128 v[162:165], v144 offset:1024
	ds_read_b128 v[166:169], v144 offset:2048
	ds_read_b128 v[170:173], v144 offset:3072
	ds_read_b128 v[174:177], v144 offset:16384
	ds_read_b128 v[178:181], v144 offset:17408
	ds_read_b128 v[182:185], v144 offset:18432
	ds_read_b128 v[186:189], v144 offset:19456
	s_add_i32 m0, s53, 0xe000
	s_nop 0
	global_load_lds_dwordx4 v140, s[20:21]
	ds_read_b128 v[190:193], v155
	ds_read_b128 v[206:209], v155 offset:1024
	ds_read_b128 v[210:213], v155 offset:2048
	ds_read_b128 v[214:217], v155 offset:3072
	ds_read_b128 v[226:229], v155 offset:4096
	ds_read_b128 v[234:237], v155 offset:5120
	ds_read_b128 v[238:241], v155 offset:6144
	ds_read_b128 v[242:245], v155 offset:7168
	s_waitcnt vmcnt(8)
	s_waitcnt lgkmcnt(0)
	s_barrier
	s_setprio 1
	s_waitcnt lgkmcnt(0)
	v_mfma_f32_16x16x32_bf16 v[126:129], v[158:161], v[190:193], v[126:129]
	v_mfma_f32_16x16x32_bf16 v[118:121], v[166:169], v[190:193], v[118:121]
	v_mfma_f32_16x16x32_bf16 v[110:113], v[158:161], v[210:213], v[110:113]
	v_mfma_f32_16x16x32_bf16 v[102:105], v[166:169], v[210:213], v[102:105]
	v_mfma_f32_16x16x32_bf16 v[94:97], v[158:161], v[226:229], v[94:97]
	v_mfma_f32_16x16x32_bf16 v[86:89], v[166:169], v[226:229], v[86:89]
	v_mfma_f32_16x16x32_bf16 v[78:81], v[158:161], v[238:241], v[78:81]
	v_mfma_f32_16x16x32_bf16 v[70:73], v[166:169], v[238:241], v[70:73]
	v_mfma_f32_16x16x32_bf16 v[126:129], v[162:165], v[206:209], v[126:129]
	v_mfma_f32_16x16x32_bf16 v[118:121], v[170:173], v[206:209], v[118:121]
	v_mfma_f32_16x16x32_bf16 v[110:113], v[162:165], v[214:217], v[110:113]
	v_mfma_f32_16x16x32_bf16 v[102:105], v[170:173], v[214:217], v[102:105]
	v_mfma_f32_16x16x32_bf16 v[94:97], v[162:165], v[234:237], v[94:97]
	v_mfma_f32_16x16x32_bf16 v[86:89], v[170:173], v[234:237], v[86:89]
	v_mfma_f32_16x16x32_bf16 v[78:81], v[162:165], v[242:245], v[78:81]
	v_mfma_f32_16x16x32_bf16 v[70:73], v[170:173], v[242:245], v[70:73]
	s_setprio 0
	s_setprio 1
	v_mfma_f32_16x16x32_bf16 v[122:125], v[174:177], v[190:193], v[122:125]
	v_mfma_f32_16x16x32_bf16 v[114:117], v[182:185], v[190:193], v[114:117]
	v_mfma_f32_16x16x32_bf16 v[106:109], v[174:177], v[210:213], v[106:109]
	v_mfma_f32_16x16x32_bf16 v[98:101], v[182:185], v[210:213], v[98:101]
	v_mfma_f32_16x16x32_bf16 v[90:93], v[174:177], v[226:229], v[90:93]
	v_mfma_f32_16x16x32_bf16 v[82:85], v[182:185], v[226:229], v[82:85]
	v_mfma_f32_16x16x32_bf16 v[74:77], v[174:177], v[238:241], v[74:77]
	v_mfma_f32_16x16x32_bf16 v[66:69], v[182:185], v[238:241], v[66:69]
	v_mfma_f32_16x16x32_bf16 v[122:125], v[178:181], v[206:209], v[122:125]
	v_mfma_f32_16x16x32_bf16 v[114:117], v[186:189], v[206:209], v[114:117]
	v_mfma_f32_16x16x32_bf16 v[106:109], v[178:181], v[214:217], v[106:109]
	v_mfma_f32_16x16x32_bf16 v[98:101], v[186:189], v[214:217], v[98:101]
	v_mfma_f32_16x16x32_bf16 v[90:93], v[178:181], v[234:237], v[90:93]
	v_mfma_f32_16x16x32_bf16 v[82:85], v[186:189], v[234:237], v[82:85]
	v_mfma_f32_16x16x32_bf16 v[74:77], v[178:181], v[242:245], v[74:77]
	v_mfma_f32_16x16x32_bf16 v[66:69], v[186:189], v[242:245], v[66:69]
	s_setprio 0
	s_barrier
	s_add_i32 s76, s76, s41
	s_mov_b32 m0, s76
	s_nop 0
	global_load_lds_dwordx4 v132, s[42:43]
	ds_read_b128 v[190:193], v155 offset:16384
	ds_read_b128 v[206:209], v155 offset:17408
	s_add_i32 m0, s76, 0x2000
	s_add_u32 s76, s42, 0x80000
	s_addc_u32 s77, s43, 0
	s_add_i32 s79, s79, s41
	global_load_lds_dwordx4 v136, s[42:43]
	ds_read_b128 v[210:213], v155 offset:18432
	ds_read_b128 v[214:217], v155 offset:19456
	ds_read_b128 v[226:229], v155 offset:20480
	ds_read_b128 v[234:237], v155 offset:21504
	ds_read_b128 v[238:241], v155 offset:22528
	ds_read_b128 v[242:245], v155 offset:23552
	s_mov_b32 m0, s53
	s_nop 0
	global_load_lds_dwordx4 v130, s[44:45]
	s_mov_b32 m0, s56
	s_nop 0
	global_load_lds_dwordx4 v134, s[44:45]
	s_waitcnt vmcnt(6)
	s_waitcnt lgkmcnt(0)
	s_barrier
	s_setprio 1
	s_waitcnt lgkmcnt(0)
	v_mfma_f32_16x16x32_bf16 v[62:65], v[158:161], v[190:193], v[62:65]
	v_mfma_f32_16x16x32_bf16 v[54:57], v[166:169], v[190:193], v[54:57]
	v_mfma_f32_16x16x32_bf16 v[46:49], v[158:161], v[210:213], v[46:49]
	v_mfma_f32_16x16x32_bf16 v[38:41], v[166:169], v[210:213], v[38:41]
	v_mfma_f32_16x16x32_bf16 v[30:33], v[158:161], v[226:229], v[30:33]
	v_mfma_f32_16x16x32_bf16 v[22:25], v[166:169], v[226:229], v[22:25]
	v_mfma_f32_16x16x32_bf16 v[14:17], v[158:161], v[238:241], v[14:17]
	v_mfma_f32_16x16x32_bf16 v[6:9], v[166:169], v[238:241], v[6:9]
	v_mfma_f32_16x16x32_bf16 v[62:65], v[162:165], v[206:209], v[62:65]
	v_mfma_f32_16x16x32_bf16 v[54:57], v[170:173], v[206:209], v[54:57]
	v_mfma_f32_16x16x32_bf16 v[46:49], v[162:165], v[214:217], v[46:49]
	v_mfma_f32_16x16x32_bf16 v[38:41], v[170:173], v[214:217], v[38:41]
	v_mfma_f32_16x16x32_bf16 v[30:33], v[162:165], v[234:237], v[30:33]
	v_mfma_f32_16x16x32_bf16 v[22:25], v[170:173], v[234:237], v[22:25]
	v_mfma_f32_16x16x32_bf16 v[14:17], v[162:165], v[242:245], v[14:17]
	v_mfma_f32_16x16x32_bf16 v[6:9], v[170:173], v[242:245], v[6:9]
	s_setprio 0
	s_setprio 1
	v_mfma_f32_16x16x32_bf16 v[58:61], v[174:177], v[190:193], v[58:61]
	v_mfma_f32_16x16x32_bf16 v[50:53], v[182:185], v[190:193], v[50:53]
	v_mfma_f32_16x16x32_bf16 v[42:45], v[174:177], v[210:213], v[42:45]
	v_mfma_f32_16x16x32_bf16 v[34:37], v[182:185], v[210:213], v[34:37]
	v_mfma_f32_16x16x32_bf16 v[26:29], v[174:177], v[226:229], v[26:29]
	v_mfma_f32_16x16x32_bf16 v[18:21], v[182:185], v[226:229], v[18:21]
	v_mfma_f32_16x16x32_bf16 v[10:13], v[174:177], v[238:241], v[10:13]
	v_mfma_f32_16x16x32_bf16 v[2:5], v[182:185], v[238:241], v[2:5]
	v_mfma_f32_16x16x32_bf16 v[58:61], v[178:181], v[206:209], v[58:61]
	v_mfma_f32_16x16x32_bf16 v[50:53], v[186:189], v[206:209], v[50:53]
	v_mfma_f32_16x16x32_bf16 v[42:45], v[178:181], v[214:217], v[42:45]
	v_mfma_f32_16x16x32_bf16 v[34:37], v[186:189], v[214:217], v[34:37]
	v_mfma_f32_16x16x32_bf16 v[26:29], v[178:181], v[234:237], v[26:29]
	v_mfma_f32_16x16x32_bf16 v[18:21], v[186:189], v[234:237], v[18:21]
	v_mfma_f32_16x16x32_bf16 v[10:13], v[178:181], v[242:245], v[10:13]
	v_mfma_f32_16x16x32_bf16 v[2:5], v[186:189], v[242:245], v[2:5]
	s_setprio 0
	s_barrier
; #define PG8_STAGE(bufoff, gbase, voff) do { _Pragma("unroll") for (int _i = 0; _i < 2; ++_i) \
;         __builtin_amdgcn_global_load_lds((const unsigned*)((const char*)(gbase) + (voff)[_i]), (PG8_LAS unsigned*)(lds + (bufoff) + ldsw + _i * 8192), 16, 0, 0); } while (0)
; #define PG8_LDA(dst, b, h) do { _Pragma("unroll") for (int m = 0; m < 4; ++m) _Pragma("unroll") for (int k = 0; k < 2; ++k) dst[m][k] = *(const PG8_LAS bf16x8*)(lds + PG8_SA(b, h) + aoff + m * 2048 + k * 1024); } while (0)
; #define PG8_LDB(dst, b, h) do { _Pragma("unroll") for (int n = 0; n < 2; ++n) _Pragma("unroll") for (int k = 0; k < 2; ++k) dst[n][k] = *(const PG8_LAS bf16x8*)(lds + PG8_SB(b, h) + boff + n * 2048 + k * 1024); } while (0)
; #define PG8_MMA(ai, bj, At, Bt) do { __builtin_amdgcn_s_setprio(1); _Pragma("unroll") for (int m = 0; m < 4; ++m) _Pragma("unroll") for (int n = 0; n < 2; ++n) _Pragma("unroll") for (int k = 0; k < 2; ++k) \
;         acc[ai][bj][m][n] = __builtin_amdgcn_mfma_f32_16x16x32_bf16(Bt[n][k], At[m][k], acc[ai][bj][m][n], 0, 0, 0); __builtin_amdgcn_s_setprio(0); } while (0)
; #define PG8_WAIT_V(n) asm volatile("s_waitcnt vmcnt(" #n ")" ::: "memory")
; #define PG8_WAIT_L(n) asm volatile("s_waitcnt lgkmcnt(" #n ")" ::: "memory")
; #define PG8_BAR __builtin_amdgcn_s_barrier()
; #define PG8_SCHED __builtin_amdgcn_sched_barrier(0)
; template <class Epi, class Sched, bool ALIGN_EPI = false, bool SP2 = false>
; __device__ __forceinline__ void gemm_phase(PG8_LAS unsigned char* lds, const Gemm g, const Sched& S, const Epi& E, const int wave_id) {
;     ...
;             PG8_LDB(B0, 1, 0); PG8_LDB(B1, 1, 1); PG8_SCHED; PG8_LDA(At, 1, 0); PG8_STAGE(PG8_SA(0, 1), a2 + hstep, voffA);
;             PG8_WAIT_V(8); PG8_WAIT_L(0); PG8_BAR; PG8_MMA(0, 0, At, B0); PG8_MMA(0, 1, At, B1); PG8_BAR; PG8_SCHED;
;             PG8_LDA(At, 1, 1); PG8_STAGE(PG8_SB(1, 0), b3, voffB); PG8_STAGE(PG8_SB(1, 1), b3 + hstep, voffB); PG8_STAGE(PG8_SA(1, 0), a3, voffA);
;             PG8_WAIT_V(8); PG8_WAIT_L(0); PG8_BAR; PG8_MMA(1, 0, At, B0); PG8_MMA(1, 1, At, B1); PG8_BAR; PG8_SCHED;
;     ...
;         if constexpr (ALIGN_EPI) { if (wr == 0) PG8_BAR; }
	s_mov_b32 m0, s79
	s_nop 0
	global_load_lds_dwordx4 v132, s[76:77]
	s_add_i32 m0, s79, 0x2000
	s_nop 0
	global_load_lds_dwordx4 v136, s[76:77]
	s_add_i32 s76, 0, 0x18000
	s_add_i32 s77, 0, 0x1c000
	s_add_u32 s44, s44, 0x80000
	s_addc_u32 s45, s45, 0
	s_mov_b32 m0, s57
	s_nop 0
	global_load_lds_dwordx4 v130, s[44:45]
	ds_read_b128 v[158:161], v144 offset:32768
	ds_read_b128 v[162:165], v144 offset:33792
	ds_read_b128 v[166:169], v144 offset:34816
	ds_read_b128 v[170:173], v144 offset:35840
	ds_read_b128 v[174:177], v144 offset:49152
	ds_read_b128 v[178:181], v144 offset:50176
	ds_read_b128 v[182:185], v144 offset:51200
	ds_read_b128 v[186:189], v144 offset:52224
	s_mov_b32 m0, s64
	s_nop 0
	global_load_lds_dwordx4 v134, s[44:45]
	ds_read_b128 v[190:193], v155 offset:32768
	ds_read_b128 v[206:209], v155 offset:33792
	ds_read_b128 v[210:213], v155 offset:34816
	ds_read_b128 v[214:217], v155 offset:35840
	ds_read_b128 v[226:229], v155 offset:36864
	ds_read_b128 v[234:237], v155 offset:37888
	ds_read_b128 v[238:241], v155 offset:38912
	ds_read_b128 v[242:245], v155 offset:39936
	s_waitcnt vmcnt(8)
	s_waitcnt lgkmcnt(0)
	s_barrier
	s_setprio 1
	s_waitcnt lgkmcnt(0)
	v_mfma_f32_16x16x32_bf16 v[126:129], v[158:161], v[190:193], v[126:129]
	v_mfma_f32_16x16x32_bf16 v[118:121], v[166:169], v[190:193], v[118:121]
	v_mfma_f32_16x16x32_bf16 v[110:113], v[158:161], v[210:213], v[110:113]
	v_mfma_f32_16x16x32_bf16 v[102:105], v[166:169], v[210:213], v[102:105]
	v_mfma_f32_16x16x32_bf16 v[94:97], v[158:161], v[226:229], v[94:97]
	v_mfma_f32_16x16x32_bf16 v[86:89], v[166:169], v[226:229], v[86:89]
	v_mfma_f32_16x16x32_bf16 v[78:81], v[158:161], v[238:241], v[78:81]
	v_mfma_f32_16x16x32_bf16 v[70:73], v[166:169], v[238:241], v[70:73]
	v_mfma_f32_16x16x32_bf16 v[126:129], v[162:165], v[206:209], v[126:129]
	v_mfma_f32_16x16x32_bf16 v[118:121], v[170:173], v[206:209], v[118:121]
	v_mfma_f32_16x16x32_bf16 v[110:113], v[162:165], v[214:217], v[110:113]
	v_mfma_f32_16x16x32_bf16 v[102:105], v[170:173], v[214:217], v[102:105]
	v_mfma_f32_16x16x32_bf16 v[94:97], v[162:165], v[234:237], v[94:97]
	v_mfma_f32_16x16x32_bf16 v[86:89], v[170:173], v[234:237], v[86:89]
	v_mfma_f32_16x16x32_bf16 v[78:81], v[162:165], v[242:245], v[78:81]
	v_mfma_f32_16x16x32_bf16 v[70:73], v[170:173], v[242:245], v[70:73]
	s_setprio 0
	s_setprio 1
	v_mfma_f32_16x16x32_bf16 v[122:125], v[174:177], v[190:193], v[122:125]
	v_mfma_f32_16x16x32_bf16 v[114:117], v[182:185], v[190:193], v[114:117]
	v_mfma_f32_16x16x32_bf16 v[106:109], v[174:177], v[210:213], v[106:109]
	v_mfma_f32_16x16x32_bf16 v[98:101], v[182:185], v[210:213], v[98:101]
	v_mfma_f32_16x16x32_bf16 v[90:93], v[174:177], v[226:229], v[90:93]
	v_mfma_f32_16x16x32_bf16 v[82:85], v[182:185], v[226:229], v[82:85]
	v_mfma_f32_16x16x32_bf16 v[74:77], v[174:177], v[238:241], v[74:77]
	v_mfma_f32_16x16x32_bf16 v[66:69], v[182:185], v[238:241], v[66:69]
	v_mfma_f32_16x16x32_bf16 v[122:125], v[178:181], v[206:209], v[122:125]
	v_mfma_f32_16x16x32_bf16 v[114:117], v[186:189], v[206:209], v[114:117]
	v_mfma_f32_16x16x32_bf16 v[106:109], v[178:181], v[214:217], v[106:109]
	v_mfma_f32_16x16x32_bf16 v[98:101], v[186:189], v[214:217], v[98:101]
	v_mfma_f32_16x16x32_bf16 v[90:93], v[178:181], v[234:237], v[90:93]
	v_mfma_f32_16x16x32_bf16 v[82:85], v[186:189], v[234:237], v[82:85]
	v_mfma_f32_16x16x32_bf16 v[74:77], v[178:181], v[242:245], v[74:77]
	v_mfma_f32_16x16x32_bf16 v[66:69], v[186:189], v[242:245], v[66:69]
	s_setprio 0
	s_barrier
	s_add_u32 vcc_lo, s44, 0xfff80080
	s_addc_u32 vcc_hi, s45, -1
	s_mov_b32 m0, s65
	s_nop 0
	global_load_lds_dwordx4 v130, vcc
	ds_read_b128 v[190:193], v155 offset:49152
	ds_read_b128 v[206:209], v155 offset:50176
	s_mov_b32 m0, s68
	s_add_i32 s44, s76, s41
	global_load_lds_dwordx4 v134, vcc
	ds_read_b128 v[210:213], v155 offset:51200
	ds_read_b128 v[214:217], v155 offset:52224
	s_add_u32 vcc_lo, s42, 0x80
	s_addc_u32 vcc_hi, s43, 0
	s_mov_b32 m0, s44
	s_nop 0
	global_load_lds_dwordx4 v132, vcc
	ds_read_b128 v[226:229], v155 offset:53248
	ds_read_b128 v[234:237], v155 offset:54272
	s_add_i32 m0, s44, 0x2000
	s_add_u32 s42, s42, 0x80080
	s_addc_u32 s43, s43, 0
	global_load_lds_dwordx4 v136, vcc
	ds_read_b128 v[238:241], v155 offset:55296
	ds_read_b128 v[242:245], v155 offset:56320
	s_add_i32 s44, s77, s41
	s_mov_b32 m0, s44
	s_nop 0
	global_load_lds_dwordx4 v132, s[42:43]
	s_add_i32 m0, s44, 0x2000
	s_nop 0
	global_load_lds_dwordx4 v136, s[42:43]
	s_waitcnt vmcnt(8)
	s_waitcnt lgkmcnt(0)
	s_barrier
	s_setprio 1
	s_waitcnt lgkmcnt(0)
	v_mfma_f32_16x16x32_bf16 v[62:65], v[158:161], v[190:193], v[62:65]
	v_mfma_f32_16x16x32_bf16 v[54:57], v[166:169], v[190:193], v[54:57]
	v_mfma_f32_16x16x32_bf16 v[46:49], v[158:161], v[210:213], v[46:49]
	v_mfma_f32_16x16x32_bf16 v[38:41], v[166:169], v[210:213], v[38:41]
	v_mfma_f32_16x16x32_bf16 v[30:33], v[158:161], v[226:229], v[30:33]
	v_mfma_f32_16x16x32_bf16 v[22:25], v[166:169], v[226:229], v[22:25]
	v_mfma_f32_16x16x32_bf16 v[14:17], v[158:161], v[238:241], v[14:17]
	v_mfma_f32_16x16x32_bf16 v[6:9], v[166:169], v[238:241], v[6:9]
	v_mfma_f32_16x16x32_bf16 v[62:65], v[162:165], v[206:209], v[62:65]
	v_mfma_f32_16x16x32_bf16 v[54:57], v[170:173], v[206:209], v[54:57]
	v_mfma_f32_16x16x32_bf16 v[46:49], v[162:165], v[214:217], v[46:49]
	v_mfma_f32_16x16x32_bf16 v[38:41], v[170:173], v[214:217], v[38:41]
	v_mfma_f32_16x16x32_bf16 v[30:33], v[162:165], v[234:237], v[30:33]
	v_mfma_f32_16x16x32_bf16 v[22:25], v[170:173], v[234:237], v[22:25]
	v_mfma_f32_16x16x32_bf16 v[14:17], v[162:165], v[242:245], v[14:17]
	v_mfma_f32_16x16x32_bf16 v[6:9], v[170:173], v[242:245], v[6:9]
	s_setprio 0
	s_setprio 1
	v_mfma_f32_16x16x32_bf16 v[58:61], v[174:177], v[190:193], v[58:61]
	v_mfma_f32_16x16x32_bf16 v[50:53], v[182:185], v[190:193], v[50:53]
	v_mfma_f32_16x16x32_bf16 v[42:45], v[174:177], v[210:213], v[42:45]
	v_mfma_f32_16x16x32_bf16 v[34:37], v[182:185], v[210:213], v[34:37]
	v_mfma_f32_16x16x32_bf16 v[26:29], v[174:177], v[226:229], v[26:29]
	v_mfma_f32_16x16x32_bf16 v[18:21], v[182:185], v[226:229], v[18:21]
	v_mfma_f32_16x16x32_bf16 v[10:13], v[174:177], v[238:241], v[10:13]
	v_mfma_f32_16x16x32_bf16 v[2:5], v[182:185], v[238:241], v[2:5]
	v_mfma_f32_16x16x32_bf16 v[58:61], v[178:181], v[206:209], v[58:61]
	v_mfma_f32_16x16x32_bf16 v[50:53], v[186:189], v[206:209], v[50:53]
	v_mfma_f32_16x16x32_bf16 v[42:45], v[178:181], v[214:217], v[42:45]
	v_mfma_f32_16x16x32_bf16 v[34:37], v[186:189], v[214:217], v[34:37]
	v_mfma_f32_16x16x32_bf16 v[26:29], v[178:181], v[234:237], v[26:29]
	v_mfma_f32_16x16x32_bf16 v[18:21], v[186:189], v[234:237], v[18:21]
	v_mfma_f32_16x16x32_bf16 v[10:13], v[178:181], v[242:245], v[10:13]
	v_mfma_f32_16x16x32_bf16 v[2:5], v[186:189], v[242:245], v[2:5]
	s_setprio 0
	s_barrier
	s_add_i32 s75, s75, 2
	s_add_u32 s20, s20, 0x100
	s_addc_u32 s21, s21, 0
	s_add_u32 s73, s73, 0x100
	s_addc_u32 s74, s74, 0
	s_cmp_gt_u32 s75, 29
	s_cbranch_scc0 .LBB0_641
	s_and_b64 vcc, exec, s[10:11]
	s_cbranch_vccz .LBB0_644
	s_barrier

; #define PG8_STAGE(bufoff, gbase, voff) do { _Pragma("unroll") for (int _i = 0; _i < 2; ++_i) \
;         __builtin_amdgcn_global_load_lds((const unsigned*)((const char*)(gbase) + (voff)[_i]), (PG8_LAS unsigned*)(lds + (bufoff) + ldsw + _i * 8192), 16, 0, 0); } while (0)
; #define PG8_LDA(dst, b, h) do { _Pragma("unroll") for (int m = 0; m < 4; ++m) _Pragma("unroll") for (int k = 0; k < 2; ++k) dst[m][k] = *(const PG8_LAS bf16x8*)(lds + PG8_SA(b, h) + aoff + m * 2048 + k * 1024); } while (0)
; #define PG8_LDB(dst, b, h) do { _Pragma("unroll") for (int n = 0; n < 2; ++n) _Pragma("unroll") for (int k = 0; k < 2; ++k) dst[n][k] = *(const PG8_LAS bf16x8*)(lds + PG8_SB(b, h) + boff + n * 2048 + k * 1024); } while (0)
; #define PG8_MMA(ai, bj, At, Bt) do { __builtin_amdgcn_s_setprio(1); _Pragma("unroll") for (int m = 0; m < 4; ++m) _Pragma("unroll") for (int n = 0; n < 2; ++n) _Pragma("unroll") for (int k = 0; k < 2; ++k) \
;         acc[ai][bj][m][n] = __builtin_amdgcn_mfma_f32_16x16x32_bf16(Bt[n][k], At[m][k], acc[ai][bj][m][n], 0, 0, 0); __builtin_amdgcn_s_setprio(0); } while (0)
; #define PG8_WAIT_V(n) asm volatile("s_waitcnt vmcnt(" #n ")" ::: "memory")
; #define PG8_BAR __builtin_amdgcn_s_barrier()
; template <class Epi, class Sched, bool ALIGN_EPI = false, bool SP2 = false>
; __device__ __forceinline__ void gemm_phase(PG8_LAS unsigned char* lds, const Gemm g, const Sched& S, const Epi& E, const int wave_id) {
;     ...
;         for (int t = 0; t < nt; t += 2) {
;             const bool last = (t == nt - 2);
;             const char* a1 = cA + (size_t)(t + 1) * kstep;
;             const char* a2 = last ? nA : cA + (size_t)(t + 2) * kstep; const char* b2 = last ? nB : cB + (size_t)(t + 2) * kstep;
;             const char* a3 = a2 + kstep; const char* b3 = b2 + kstep;
;             if (last && has_next) S.a_ready(nxt);
;             if constexpr (SP2) {
;             PG8_LDB(B0, 0, 0); PG8_LDB(B1, 0, 1); PG8_SCHED; PG8_LDA(At, 0, 0); PG8_STAGE(PG8_SA(1, 1), a1 + hstep, voffA);
;             PG8_WAIT_V(8); PG8_WAIT_L(0); PG8_BAR; PG8_MMA(0, 0, At, B0); PG8_MMA(0, 1, At, B1); PG8_BAR; PG8_SCHED;
;             PG8_LDA(At, 0, 1); PG8_STAGE(PG8_SB(0, 0), b2, voffB); PG8_STAGE(PG8_SB(0, 1), b2 + hstep, voffB); PG8_STAGE(PG8_SA(0, 0), a2, voffA);
;             PG8_WAIT_V(8); PG8_WAIT_L(0); PG8_BAR; PG8_MMA(1, 0, At, B0); PG8_MMA(1, 1, At, B1); PG8_BAR; PG8_SCHED;
.LBB0_759:
	s_add_u32 s20, s18, 0x100
	s_addc_u32 s21, s19, 0
	s_add_i32 s77, 0, 0x10000
	s_cmpk_eq_i32 s76, 0x54
	s_cselect_b32 s43, s15, s21
	s_cselect_b32 s42, s14, s20
	s_cselect_b32 s41, s17, s75
	s_cselect_b32 s40, s16, s74
	s_add_i32 s79, 0, 0x14000
	s_add_i32 m0, s52, 0xc000
	s_nop 0
	global_load_lds_dwordx4 v210, s[18:19]
	ds_read_b128 v[118:121], v226
	ds_read_b128 v[122:125], v226 offset:1024
	ds_read_b128 v[130:133], v226 offset:2048
	ds_read_b128 v[134:137], v226 offset:3072
	ds_read_b128 v[146:149], v226 offset:16384
	ds_read_b128 v[150:153], v226 offset:17408
	ds_read_b128 v[154:157], v226 offset:18432
	ds_read_b128 v[158:161], v226 offset:19456
	s_add_i32 m0, s52, 0xe000
	s_nop 0
	global_load_lds_dwordx4 v212, s[18:19]
	ds_read_b128 v[162:165], v222
	ds_read_b128 v[166:169], v222 offset:1024
	ds_read_b128 v[170:173], v222 offset:2048
	ds_read_b128 v[174:177], v222 offset:3072
	ds_read_b128 v[178:181], v222 offset:4096
	ds_read_b128 v[182:185], v222 offset:5120
	ds_read_b128 v[186:189], v222 offset:6144
	ds_read_b128 v[214:217], v222 offset:7168
	s_waitcnt vmcnt(8)
	s_waitcnt lgkmcnt(0)
	s_barrier
	s_setprio 1
	s_waitcnt lgkmcnt(0)
	v_mfma_f32_16x16x32_bf16 v[142:145], v[118:121], v[162:165], v[142:145]
	v_mfma_f32_16x16x32_bf16 v[138:141], v[130:133], v[162:165], v[138:141]
	v_mfma_f32_16x16x32_bf16 v[110:113], v[118:121], v[170:173], v[110:113]
	v_mfma_f32_16x16x32_bf16 v[106:109], v[130:133], v[170:173], v[106:109]
	v_mfma_f32_16x16x32_bf16 v[94:97], v[118:121], v[178:181], v[94:97]
	v_mfma_f32_16x16x32_bf16 v[90:93], v[130:133], v[178:181], v[90:93]
	v_mfma_f32_16x16x32_bf16 v[78:81], v[118:121], v[186:189], v[78:81]
	v_mfma_f32_16x16x32_bf16 v[74:77], v[130:133], v[186:189], v[74:77]
	v_mfma_f32_16x16x32_bf16 v[142:145], v[122:125], v[166:169], v[142:145]
	v_mfma_f32_16x16x32_bf16 v[138:141], v[134:137], v[166:169], v[138:141]
	v_mfma_f32_16x16x32_bf16 v[110:113], v[122:125], v[174:177], v[110:113]
	v_mfma_f32_16x16x32_bf16 v[106:109], v[134:137], v[174:177], v[106:109]
	v_mfma_f32_16x16x32_bf16 v[94:97], v[122:125], v[182:185], v[94:97]
	v_mfma_f32_16x16x32_bf16 v[90:93], v[134:137], v[182:185], v[90:93]
	v_mfma_f32_16x16x32_bf16 v[78:81], v[122:125], v[214:217], v[78:81]
	v_mfma_f32_16x16x32_bf16 v[74:77], v[134:137], v[214:217], v[74:77]
	s_setprio 0
	s_setprio 1
	v_mfma_f32_16x16x32_bf16 v[126:129], v[146:149], v[162:165], v[126:129]
	v_mfma_f32_16x16x32_bf16 v[114:117], v[154:157], v[162:165], v[114:117]
	v_mfma_f32_16x16x32_bf16 v[102:105], v[146:149], v[170:173], v[102:105]
	v_mfma_f32_16x16x32_bf16 v[98:101], v[154:157], v[170:173], v[98:101]
	v_mfma_f32_16x16x32_bf16 v[86:89], v[146:149], v[178:181], v[86:89]
	v_mfma_f32_16x16x32_bf16 v[82:85], v[154:157], v[178:181], v[82:85]
	v_mfma_f32_16x16x32_bf16 v[70:73], v[146:149], v[186:189], v[70:73]
	v_mfma_f32_16x16x32_bf16 v[66:69], v[154:157], v[186:189], v[66:69]
	v_mfma_f32_16x16x32_bf16 v[126:129], v[150:153], v[166:169], v[126:129]
	v_mfma_f32_16x16x32_bf16 v[114:117], v[158:161], v[166:169], v[114:117]
	v_mfma_f32_16x16x32_bf16 v[102:105], v[150:153], v[174:177], v[102:105]
	v_mfma_f32_16x16x32_bf16 v[98:101], v[158:161], v[174:177], v[98:101]
	v_mfma_f32_16x16x32_bf16 v[86:89], v[150:153], v[182:185], v[86:89]
	v_mfma_f32_16x16x32_bf16 v[82:85], v[158:161], v[182:185], v[82:85]
	v_mfma_f32_16x16x32_bf16 v[70:73], v[150:153], v[214:217], v[70:73]
	v_mfma_f32_16x16x32_bf16 v[66:69], v[158:161], v[214:217], v[66:69]
	s_setprio 0
	s_barrier
	s_add_i32 s18, s77, s49
	s_mov_b32 m0, s18
	s_nop 0
	global_load_lds_dwordx4 v192, s[40:41]
	ds_read_b128 v[162:165], v222 offset:16384
	ds_read_b128 v[166:169], v222 offset:17408
	s_add_i32 m0, s18, 0x2000
	s_add_u32 s18, s40, 0x160000
	s_addc_u32 s19, s41, 0
	s_add_i32 s77, s79, s49
	global_load_lds_dwordx4 v208, s[40:41]
	ds_read_b128 v[170:173], v222 offset:18432
	ds_read_b128 v[174:177], v222 offset:19456
	ds_read_b128 v[178:181], v222 offset:20480
	ds_read_b128 v[182:185], v222 offset:21504
	ds_read_b128 v[186:189], v222 offset:22528
	ds_read_b128 v[214:217], v222 offset:23552
	s_mov_b32 m0, s52
	s_nop 0
	global_load_lds_dwordx4 v190, s[42:43]
	s_mov_b32 m0, s53
	s_nop 0
	global_load_lds_dwordx4 v206, s[42:43]
	s_waitcnt vmcnt(6)
	s_waitcnt lgkmcnt(0)
	s_barrier
	s_setprio 1
	s_waitcnt lgkmcnt(0)
	v_mfma_f32_16x16x32_bf16 v[62:65], v[118:121], v[162:165], v[62:65]
	v_mfma_f32_16x16x32_bf16 v[58:61], v[130:133], v[162:165], v[58:61]
	v_mfma_f32_16x16x32_bf16 v[46:49], v[118:121], v[170:173], v[46:49]
	v_mfma_f32_16x16x32_bf16 v[42:45], v[130:133], v[170:173], v[42:45]
	v_mfma_f32_16x16x32_bf16 v[30:33], v[118:121], v[178:181], v[30:33]
	v_mfma_f32_16x16x32_bf16 v[26:29], v[130:133], v[178:181], v[26:29]
	v_mfma_f32_16x16x32_bf16 v[14:17], v[118:121], v[186:189], v[14:17]
	v_mfma_f32_16x16x32_bf16 v[10:13], v[130:133], v[186:189], v[10:13]
	v_mfma_f32_16x16x32_bf16 v[62:65], v[122:125], v[166:169], v[62:65]
	v_mfma_f32_16x16x32_bf16 v[58:61], v[134:137], v[166:169], v[58:61]
	v_mfma_f32_16x16x32_bf16 v[46:49], v[122:125], v[174:177], v[46:49]
	v_mfma_f32_16x16x32_bf16 v[42:45], v[134:137], v[174:177], v[42:45]
	v_mfma_f32_16x16x32_bf16 v[30:33], v[122:125], v[182:185], v[30:33]
	v_mfma_f32_16x16x32_bf16 v[26:29], v[134:137], v[182:185], v[26:29]
	v_mfma_f32_16x16x32_bf16 v[14:17], v[122:125], v[214:217], v[14:17]
	v_mfma_f32_16x16x32_bf16 v[10:13], v[134:137], v[214:217], v[10:13]
	s_setprio 0
	s_setprio 1
	v_mfma_f32_16x16x32_bf16 v[54:57], v[146:149], v[162:165], v[54:57]
	v_mfma_f32_16x16x32_bf16 v[50:53], v[154:157], v[162:165], v[50:53]
	v_mfma_f32_16x16x32_bf16 v[38:41], v[146:149], v[170:173], v[38:41]
	v_mfma_f32_16x16x32_bf16 v[34:37], v[154:157], v[170:173], v[34:37]
	v_mfma_f32_16x16x32_bf16 v[22:25], v[146:149], v[178:181], v[22:25]
	v_mfma_f32_16x16x32_bf16 v[18:21], v[154:157], v[178:181], v[18:21]
	v_mfma_f32_16x16x32_bf16 v[6:9], v[146:149], v[186:189], v[6:9]
	v_mfma_f32_16x16x32_bf16 v[2:5], v[154:157], v[186:189], v[2:5]
	v_mfma_f32_16x16x32_bf16 v[54:57], v[150:153], v[166:169], v[54:57]
	v_mfma_f32_16x16x32_bf16 v[50:53], v[158:161], v[166:169], v[50:53]
	v_mfma_f32_16x16x32_bf16 v[38:41], v[150:153], v[174:177], v[38:41]
	v_mfma_f32_16x16x32_bf16 v[34:37], v[158:161], v[174:177], v[34:37]
	v_mfma_f32_16x16x32_bf16 v[22:25], v[150:153], v[182:185], v[22:25]
	v_mfma_f32_16x16x32_bf16 v[18:21], v[158:161], v[182:185], v[18:21]
	v_mfma_f32_16x16x32_bf16 v[6:9], v[150:153], v[214:217], v[6:9]
	v_mfma_f32_16x16x32_bf16 v[2:5], v[158:161], v[214:217], v[2:5]
	s_setprio 0
	s_barrier
; #define PG8_STAGE(bufoff, gbase, voff) do { _Pragma("unroll") for (int _i = 0; _i < 2; ++_i) \
;         __builtin_amdgcn_global_load_lds((const unsigned*)((const char*)(gbase) + (voff)[_i]), (PG8_LAS unsigned*)(lds + (bufoff) + ldsw + _i * 8192), 16, 0, 0); } while (0)
; #define PG8_LDA(dst, b, h) do { _Pragma("unroll") for (int m = 0; m < 4; ++m) _Pragma("unroll") for (int k = 0; k < 2; ++k) dst[m][k] = *(const PG8_LAS bf16x8*)(lds + PG8_SA(b, h) + aoff + m * 2048 + k * 1024); } while (0)
; #define PG8_LDB(dst, b, h) do { _Pragma("unroll") for (int n = 0; n < 2; ++n) _Pragma("unroll") for (int k = 0; k < 2; ++k) dst[n][k] = *(const PG8_LAS bf16x8*)(lds + PG8_SB(b, h) + boff + n * 2048 + k * 1024); } while (0)
; #define PG8_MMA(ai, bj, At, Bt) do { __builtin_amdgcn_s_setprio(1); _Pragma("unroll") for (int m = 0; m < 4; ++m) _Pragma("unroll") for (int n = 0; n < 2; ++n) _Pragma("unroll") for (int k = 0; k < 2; ++k) \
;         acc[ai][bj][m][n] = __builtin_amdgcn_mfma_f32_16x16x32_bf16(Bt[n][k], At[m][k], acc[ai][bj][m][n], 0, 0, 0); __builtin_amdgcn_s_setprio(0); } while (0)
; #define PG8_WAIT_V(n) asm volatile("s_waitcnt vmcnt(" #n ")" ::: "memory")
; #define PG8_WAIT_L(n) asm volatile("s_waitcnt lgkmcnt(" #n ")" ::: "memory")
; #define PG8_BAR __builtin_amdgcn_s_barrier()
; #define PG8_SCHED __builtin_amdgcn_sched_barrier(0)
; template <class Epi, class Sched, bool ALIGN_EPI = false, bool SP2 = false>
; __device__ __forceinline__ void gemm_phase(PG8_LAS unsigned char* lds, const Gemm g, const Sched& S, const Epi& E, const int wave_id) {
;     ...
;             PG8_LDB(B0, 1, 0); PG8_LDB(B1, 1, 1); PG8_SCHED; PG8_LDA(At, 1, 0); PG8_STAGE(PG8_SA(0, 1), a2 + hstep, voffA);
;             PG8_WAIT_V(8); PG8_WAIT_L(0); PG8_BAR; PG8_MMA(0, 0, At, B0); PG8_MMA(0, 1, At, B1); PG8_BAR; PG8_SCHED;
;             PG8_LDA(At, 1, 1); PG8_STAGE(PG8_SB(1, 0), b3, voffB); PG8_STAGE(PG8_SB(1, 1), b3 + hstep, voffB); PG8_STAGE(PG8_SA(1, 0), a3, voffA);
;             PG8_WAIT_V(8); PG8_WAIT_L(0); PG8_BAR; PG8_MMA(1, 0, At, B0); PG8_MMA(1, 1, At, B1); PG8_BAR; PG8_SCHED;
	s_mov_b32 m0, s77
	s_nop 0
	global_load_lds_dwordx4 v192, s[18:19]
	s_add_i32 m0, s77, 0x2000
	s_nop 0
	global_load_lds_dwordx4 v208, s[18:19]
	s_add_i32 s77, 0, 0x18000
	s_add_i32 s79, 0, 0x1c000
	s_add_u32 s18, s42, 0x160000
	s_addc_u32 s19, s43, 0
	s_mov_b32 m0, s56
	s_nop 0
	global_load_lds_dwordx4 v190, s[18:19]
	ds_read_b128 v[118:121], v226 offset:32768
	ds_read_b128 v[122:125], v226 offset:33792
	ds_read_b128 v[130:133], v226 offset:34816
	ds_read_b128 v[134:137], v226 offset:35840
	ds_read_b128 v[146:149], v226 offset:49152
	ds_read_b128 v[150:153], v226 offset:50176
	ds_read_b128 v[154:157], v226 offset:51200
	ds_read_b128 v[158:161], v226 offset:52224
	s_mov_b32 m0, s57
	s_nop 0
	global_load_lds_dwordx4 v206, s[18:19]
	ds_read_b128 v[162:165], v222 offset:32768
	ds_read_b128 v[166:169], v222 offset:33792
	ds_read_b128 v[170:173], v222 offset:34816
	ds_read_b128 v[174:177], v222 offset:35840
	ds_read_b128 v[178:181], v222 offset:36864
	ds_read_b128 v[182:185], v222 offset:37888
	ds_read_b128 v[186:189], v222 offset:38912
	ds_read_b128 v[214:217], v222 offset:39936
	s_waitcnt vmcnt(8)
	s_waitcnt lgkmcnt(0)
	s_barrier
	s_setprio 1
	s_waitcnt lgkmcnt(0)
	v_mfma_f32_16x16x32_bf16 v[142:145], v[118:121], v[162:165], v[142:145]
	v_mfma_f32_16x16x32_bf16 v[138:141], v[130:133], v[162:165], v[138:141]
	v_mfma_f32_16x16x32_bf16 v[110:113], v[118:121], v[170:173], v[110:113]
	v_mfma_f32_16x16x32_bf16 v[106:109], v[130:133], v[170:173], v[106:109]
	v_mfma_f32_16x16x32_bf16 v[94:97], v[118:121], v[178:181], v[94:97]
	v_mfma_f32_16x16x32_bf16 v[90:93], v[130:133], v[178:181], v[90:93]
	v_mfma_f32_16x16x32_bf16 v[78:81], v[118:121], v[186:189], v[78:81]
	v_mfma_f32_16x16x32_bf16 v[74:77], v[130:133], v[186:189], v[74:77]
	v_mfma_f32_16x16x32_bf16 v[142:145], v[122:125], v[166:169], v[142:145]
	v_mfma_f32_16x16x32_bf16 v[138:141], v[134:137], v[166:169], v[138:141]
	v_mfma_f32_16x16x32_bf16 v[110:113], v[122:125], v[174:177], v[110:113]
	v_mfma_f32_16x16x32_bf16 v[106:109], v[134:137], v[174:177], v[106:109]
	v_mfma_f32_16x16x32_bf16 v[94:97], v[122:125], v[182:185], v[94:97]
	v_mfma_f32_16x16x32_bf16 v[90:93], v[134:137], v[182:185], v[90:93]
	v_mfma_f32_16x16x32_bf16 v[78:81], v[122:125], v[214:217], v[78:81]
	v_mfma_f32_16x16x32_bf16 v[74:77], v[134:137], v[214:217], v[74:77]
	s_setprio 0
	s_setprio 1
	v_mfma_f32_16x16x32_bf16 v[126:129], v[146:149], v[162:165], v[126:129]
	v_mfma_f32_16x16x32_bf16 v[114:117], v[154:157], v[162:165], v[114:117]
	v_mfma_f32_16x16x32_bf16 v[102:105], v[146:149], v[170:173], v[102:105]
	v_mfma_f32_16x16x32_bf16 v[98:101], v[154:157], v[170:173], v[98:101]
	v_mfma_f32_16x16x32_bf16 v[86:89], v[146:149], v[178:181], v[86:89]
	v_mfma_f32_16x16x32_bf16 v[82:85], v[154:157], v[178:181], v[82:85]
	v_mfma_f32_16x16x32_bf16 v[70:73], v[146:149], v[186:189], v[70:73]
	v_mfma_f32_16x16x32_bf16 v[66:69], v[154:157], v[186:189], v[66:69]
	v_mfma_f32_16x16x32_bf16 v[126:129], v[150:153], v[166:169], v[126:129]
	v_mfma_f32_16x16x32_bf16 v[114:117], v[158:161], v[166:169], v[114:117]
	v_mfma_f32_16x16x32_bf16 v[102:105], v[150:153], v[174:177], v[102:105]
	v_mfma_f32_16x16x32_bf16 v[98:101], v[158:161], v[174:177], v[98:101]
	v_mfma_f32_16x16x32_bf16 v[86:89], v[150:153], v[182:185], v[86:89]
	v_mfma_f32_16x16x32_bf16 v[82:85], v[158:161], v[182:185], v[82:85]
	v_mfma_f32_16x16x32_bf16 v[70:73], v[150:153], v[214:217], v[70:73]
	v_mfma_f32_16x16x32_bf16 v[66:69], v[158:161], v[214:217], v[66:69]
	s_setprio 0
	s_barrier
	s_add_u32 vcc_lo, s42, 0x80
	s_addc_u32 vcc_hi, s43, 0
	s_mov_b32 m0, s68
	s_nop 0
	global_load_lds_dwordx4 v190, vcc
	ds_read_b128 v[162:165], v222 offset:49152
	ds_read_b128 v[166:169], v222 offset:50176
	s_mov_b32 m0, s69
	s_add_i32 s18, s77, s49
	global_load_lds_dwordx4 v206, vcc
	ds_read_b128 v[170:173], v222 offset:51200
	ds_read_b128 v[174:177], v222 offset:52224
	s_add_u32 vcc_lo, s40, 0x80
	s_addc_u32 vcc_hi, s41, 0
	s_mov_b32 m0, s18
	s_nop 0
	global_load_lds_dwordx4 v192, vcc
	ds_read_b128 v[178:181], v222 offset:53248
	ds_read_b128 v[182:185], v222 offset:54272
	s_add_i32 m0, s18, 0x2000
	s_add_u32 s18, s40, 0x160080
	s_addc_u32 s19, s41, 0
	global_load_lds_dwordx4 v208, vcc
	ds_read_b128 v[186:189], v222 offset:55296
	ds_read_b128 v[214:217], v222 offset:56320
	s_add_i32 s40, s79, s49
	s_mov_b32 m0, s40
	s_nop 0
	global_load_lds_dwordx4 v192, s[18:19]
	s_add_i32 m0, s40, 0x2000
	s_nop 0
	global_load_lds_dwordx4 v208, s[18:19]
	s_waitcnt vmcnt(8)
	s_waitcnt lgkmcnt(0)
	s_barrier
	s_setprio 1
	s_waitcnt lgkmcnt(0)
	v_mfma_f32_16x16x32_bf16 v[62:65], v[118:121], v[162:165], v[62:65]
	v_mfma_f32_16x16x32_bf16 v[58:61], v[130:133], v[162:165], v[58:61]
	v_mfma_f32_16x16x32_bf16 v[46:49], v[118:121], v[170:173], v[46:49]
	v_mfma_f32_16x16x32_bf16 v[42:45], v[130:133], v[170:173], v[42:45]
	v_mfma_f32_16x16x32_bf16 v[30:33], v[118:121], v[178:181], v[30:33]
	v_mfma_f32_16x16x32_bf16 v[26:29], v[130:133], v[178:181], v[26:29]
	v_mfma_f32_16x16x32_bf16 v[14:17], v[118:121], v[186:189], v[14:17]
	v_mfma_f32_16x16x32_bf16 v[10:13], v[130:133], v[186:189], v[10:13]
	v_mfma_f32_16x16x32_bf16 v[62:65], v[122:125], v[166:169], v[62:65]
	v_mfma_f32_16x16x32_bf16 v[58:61], v[134:137], v[166:169], v[58:61]
	v_mfma_f32_16x16x32_bf16 v[46:49], v[122:125], v[174:177], v[46:49]
	v_mfma_f32_16x16x32_bf16 v[42:45], v[134:137], v[174:177], v[42:45]
	v_mfma_f32_16x16x32_bf16 v[30:33], v[122:125], v[182:185], v[30:33]
	v_mfma_f32_16x16x32_bf16 v[26:29], v[134:137], v[182:185], v[26:29]
	v_mfma_f32_16x16x32_bf16 v[14:17], v[122:125], v[214:217], v[14:17]
	v_mfma_f32_16x16x32_bf16 v[10:13], v[134:137], v[214:217], v[10:13]
	s_setprio 0
	s_setprio 1
	v_mfma_f32_16x16x32_bf16 v[54:57], v[146:149], v[162:165], v[54:57]
	v_mfma_f32_16x16x32_bf16 v[50:53], v[154:157], v[162:165], v[50:53]
	v_mfma_f32_16x16x32_bf16 v[38:41], v[146:149], v[170:173], v[38:41]
	v_mfma_f32_16x16x32_bf16 v[34:37], v[154:157], v[170:173], v[34:37]
	v_mfma_f32_16x16x32_bf16 v[22:25], v[146:149], v[178:181], v[22:25]
	v_mfma_f32_16x16x32_bf16 v[18:21], v[154:157], v[178:181], v[18:21]
	v_mfma_f32_16x16x32_bf16 v[6:9], v[146:149], v[186:189], v[6:9]
	v_mfma_f32_16x16x32_bf16 v[2:5], v[154:157], v[186:189], v[2:5]
	v_mfma_f32_16x16x32_bf16 v[54:57], v[150:153], v[166:169], v[54:57]
	v_mfma_f32_16x16x32_bf16 v[50:53], v[158:161], v[166:169], v[50:53]
	v_mfma_f32_16x16x32_bf16 v[38:41], v[150:153], v[174:177], v[38:41]
	v_mfma_f32_16x16x32_bf16 v[34:37], v[158:161], v[174:177], v[34:37]
	v_mfma_f32_16x16x32_bf16 v[22:25], v[150:153], v[182:185], v[22:25]
	v_mfma_f32_16x16x32_bf16 v[18:21], v[158:161], v[182:185], v[18:21]
	v_mfma_f32_16x16x32_bf16 v[6:9], v[150:153], v[214:217], v[6:9]
	v_mfma_f32_16x16x32_bf16 v[2:5], v[158:161], v[214:217], v[2:5]
	s_setprio 0
	s_barrier
	s_add_i32 s76, s76, 2
	s_add_u32 s74, s74, 0x100
	s_addc_u32 s75, s75, 0
	s_cmpk_gt_u32 s76, 0x55
	s_mov_b64 s[18:19], s[20:21]
	s_cbranch_scc0 .LBB0_759
	s_and_b64 vcc, exec, s[10:11]
	s_cbranch_vccz .LBB0_762
	s_barrier

; #define PG8_STAGE(bufoff, gbase, voff) do { _Pragma("unroll") for (int _i = 0; _i < 2; ++_i) \
;         __builtin_amdgcn_global_load_lds((const unsigned*)((const char*)(gbase) + (voff)[_i]), (PG8_LAS unsigned*)(lds + (bufoff) + ldsw + _i * 8192), 16, 0, 0); } while (0)
; #define PG8_LDA(dst, b, h) do { _Pragma("unroll") for (int m = 0; m < 4; ++m) _Pragma("unroll") for (int k = 0; k < 2; ++k) dst[m][k] = *(const PG8_LAS bf16x8*)(lds + PG8_SA(b, h) + aoff + m * 2048 + k * 1024); } while (0)
; #define PG8_LDB(dst, b, h) do { _Pragma("unroll") for (int n = 0; n < 2; ++n) _Pragma("unroll") for (int k = 0; k < 2; ++k) dst[n][k] = *(const PG8_LAS bf16x8*)(lds + PG8_SB(b, h) + boff + n * 2048 + k * 1024); } while (0)
; #define PG8_MMA(ai, bj, At, Bt) do { __builtin_amdgcn_s_setprio(1); _Pragma("unroll") for (int m = 0; m < 4; ++m) _Pragma("unroll") for (int n = 0; n < 2; ++n) _Pragma("unroll") for (int k = 0; k < 2; ++k) \
;         acc[ai][bj][m][n] = __builtin_amdgcn_mfma_f32_16x16x32_bf16(Bt[n][k], At[m][k], acc[ai][bj][m][n], 0, 0, 0); __builtin_amdgcn_s_setprio(0); } while (0)
; #define PG8_WAIT_V(n) asm volatile("s_waitcnt vmcnt(" #n ")" ::: "memory")
; #define PG8_WAIT_L(n) asm volatile("s_waitcnt lgkmcnt(" #n ")" ::: "memory")
; #define PG8_BAR __builtin_amdgcn_s_barrier()
; #define PG8_SCHED __builtin_amdgcn_sched_barrier(0)
; template <class Epi, class Sched, bool ALIGN_EPI = false, bool SP2 = false>
; __device__ __forceinline__ void gemm_phase(PG8_LAS unsigned char* lds, const Gemm g, const Sched& S, const Epi& E, const int wave_id) {
;     ...
;             PG8_LDB(B0, 0, 0); PG8_LDB(B1, 0, 1); PG8_SCHED; PG8_LDA(At, 0, 0); PG8_STAGE(PG8_SA(1, 1), a1 + hstep, voffA);
;             PG8_WAIT_V(8); PG8_WAIT_L(0); PG8_BAR; PG8_MMA(0, 0, At, B0); PG8_MMA(0, 1, At, B1); PG8_BAR; PG8_SCHED;
;             PG8_LDA(At, 0, 1); PG8_STAGE(PG8_SB(0, 0), b2, voffB); PG8_STAGE(PG8_SB(0, 1), b2 + hstep, voffB); PG8_STAGE(PG8_SA(0, 0), a2, voffA);
;             PG8_WAIT_V(8); PG8_WAIT_L(0); PG8_BAR; PG8_MMA(1, 0, At, B0); PG8_MMA(1, 1, At, B1); PG8_BAR; PG8_SCHED;
.LBB0_904:
	s_add_u32 s52, s46, 0xfff80080
	s_addc_u32 s53, s47, -1
	s_add_i32 s85, 0, 0x10000
	s_cmp_eq_u32 s84, 28
	s_cselect_b32 s83, s21, s53
	s_cselect_b32 s82, s49, s52
	s_cselect_b32 s53, s19, s81
	s_cselect_b32 s52, s79, s80
	s_add_i32 s92, 0, 0x14000
	s_add_i32 m0, s70, 0xc000
	s_nop 0
	global_load_lds_dwordx4 v214, s[46:47]
	ds_read_b128 v[114:117], v226
	ds_read_b128 v[118:121], v226 offset:1024
	ds_read_b128 v[130:133], v226 offset:2048
	ds_read_b128 v[134:137], v226 offset:3072
	ds_read_b128 v[138:141], v226 offset:16384
	ds_read_b128 v[142:145], v226 offset:17408
	ds_read_b128 v[146:149], v226 offset:18432
	ds_read_b128 v[150:153], v226 offset:19456
	s_add_i32 m0, s70, 0xe000
	s_nop 0
	global_load_lds_dwordx4 v216, s[46:47]
	ds_read_b128 v[162:165], v244
	ds_read_b128 v[166:169], v244 offset:1024
	ds_read_b128 v[170:173], v244 offset:2048
	ds_read_b128 v[174:177], v244 offset:3072
	ds_read_b128 v[178:181], v244 offset:4096
	ds_read_b128 v[182:185], v244 offset:5120
	ds_read_b128 v[186:189], v244 offset:6144
	ds_read_b128 v[190:193], v244 offset:7168
	s_waitcnt vmcnt(8)
	s_waitcnt lgkmcnt(0)
	s_barrier
	s_setprio 1
	s_waitcnt lgkmcnt(0)
	v_mfma_f32_16x16x32_bf16 v[158:161], v[114:117], v[162:165], v[158:161]
	v_mfma_f32_16x16x32_bf16 v[154:157], v[130:133], v[162:165], v[154:157]
	v_mfma_f32_16x16x32_bf16 v[110:113], v[114:117], v[170:173], v[110:113]
	v_mfma_f32_16x16x32_bf16 v[106:109], v[130:133], v[170:173], v[106:109]
	v_mfma_f32_16x16x32_bf16 v[94:97], v[114:117], v[178:181], v[94:97]
	v_mfma_f32_16x16x32_bf16 v[90:93], v[130:133], v[178:181], v[90:93]
	v_mfma_f32_16x16x32_bf16 v[78:81], v[114:117], v[186:189], v[78:81]
	v_mfma_f32_16x16x32_bf16 v[74:77], v[130:133], v[186:189], v[74:77]
	v_mfma_f32_16x16x32_bf16 v[158:161], v[118:121], v[166:169], v[158:161]
	v_mfma_f32_16x16x32_bf16 v[154:157], v[134:137], v[166:169], v[154:157]
	v_mfma_f32_16x16x32_bf16 v[110:113], v[118:121], v[174:177], v[110:113]
	v_mfma_f32_16x16x32_bf16 v[106:109], v[134:137], v[174:177], v[106:109]
	v_mfma_f32_16x16x32_bf16 v[94:97], v[118:121], v[182:185], v[94:97]
	v_mfma_f32_16x16x32_bf16 v[90:93], v[134:137], v[182:185], v[90:93]
	v_mfma_f32_16x16x32_bf16 v[78:81], v[118:121], v[190:193], v[78:81]
	v_mfma_f32_16x16x32_bf16 v[74:77], v[134:137], v[190:193], v[74:77]
	s_setprio 0
	s_setprio 1
	v_mfma_f32_16x16x32_bf16 v[126:129], v[138:141], v[162:165], v[126:129]
	v_mfma_f32_16x16x32_bf16 v[122:125], v[146:149], v[162:165], v[122:125]
	v_mfma_f32_16x16x32_bf16 v[102:105], v[138:141], v[170:173], v[102:105]
	v_mfma_f32_16x16x32_bf16 v[98:101], v[146:149], v[170:173], v[98:101]
	v_mfma_f32_16x16x32_bf16 v[86:89], v[138:141], v[178:181], v[86:89]
	v_mfma_f32_16x16x32_bf16 v[82:85], v[146:149], v[178:181], v[82:85]
	v_mfma_f32_16x16x32_bf16 v[70:73], v[138:141], v[186:189], v[70:73]
	v_mfma_f32_16x16x32_bf16 v[66:69], v[146:149], v[186:189], v[66:69]
	v_mfma_f32_16x16x32_bf16 v[126:129], v[142:145], v[166:169], v[126:129]
	v_mfma_f32_16x16x32_bf16 v[122:125], v[150:153], v[166:169], v[122:125]
	v_mfma_f32_16x16x32_bf16 v[102:105], v[142:145], v[174:177], v[102:105]
	v_mfma_f32_16x16x32_bf16 v[98:101], v[150:153], v[174:177], v[98:101]
	v_mfma_f32_16x16x32_bf16 v[86:89], v[142:145], v[182:185], v[86:89]
	v_mfma_f32_16x16x32_bf16 v[82:85], v[150:153], v[182:185], v[82:85]
	v_mfma_f32_16x16x32_bf16 v[70:73], v[142:145], v[190:193], v[70:73]
	v_mfma_f32_16x16x32_bf16 v[66:69], v[150:153], v[190:193], v[66:69]
	s_setprio 0
	s_barrier
	s_add_i32 s85, s85, s69
	s_mov_b32 m0, s85
	s_nop 0
	global_load_lds_dwordx4 v208, s[52:53]
	ds_read_b128 v[162:165], v244 offset:16384
	ds_read_b128 v[166:169], v244 offset:17408
	s_add_i32 m0, s85, 0x2000
	s_add_u32 s88, s52, 0x80000
	s_addc_u32 s89, s53, 0
	s_add_i32 s85, s92, s69
	global_load_lds_dwordx4 v212, s[52:53]
	ds_read_b128 v[170:173], v244 offset:18432
	ds_read_b128 v[174:177], v244 offset:19456
	ds_read_b128 v[178:181], v244 offset:20480
	ds_read_b128 v[182:185], v244 offset:21504
	ds_read_b128 v[186:189], v244 offset:22528
	ds_read_b128 v[190:193], v244 offset:23552
	s_mov_b32 m0, s70
	s_nop 0
	global_load_lds_dwordx4 v206, s[82:83]
	s_mov_b32 m0, s71
	s_nop 0
	global_load_lds_dwordx4 v210, s[82:83]
	s_waitcnt vmcnt(6)
	s_waitcnt lgkmcnt(0)
	s_barrier
	s_setprio 1
	s_waitcnt lgkmcnt(0)
	v_mfma_f32_16x16x32_bf16 v[62:65], v[114:117], v[162:165], v[62:65]
	v_mfma_f32_16x16x32_bf16 v[58:61], v[130:133], v[162:165], v[58:61]
	v_mfma_f32_16x16x32_bf16 v[46:49], v[114:117], v[170:173], v[46:49]
	v_mfma_f32_16x16x32_bf16 v[42:45], v[130:133], v[170:173], v[42:45]
	v_mfma_f32_16x16x32_bf16 v[30:33], v[114:117], v[178:181], v[30:33]
	v_mfma_f32_16x16x32_bf16 v[26:29], v[130:133], v[178:181], v[26:29]
	v_mfma_f32_16x16x32_bf16 v[14:17], v[114:117], v[186:189], v[14:17]
	v_mfma_f32_16x16x32_bf16 v[10:13], v[130:133], v[186:189], v[10:13]
	v_mfma_f32_16x16x32_bf16 v[62:65], v[118:121], v[166:169], v[62:65]
	v_mfma_f32_16x16x32_bf16 v[58:61], v[134:137], v[166:169], v[58:61]
	v_mfma_f32_16x16x32_bf16 v[46:49], v[118:121], v[174:177], v[46:49]
	v_mfma_f32_16x16x32_bf16 v[42:45], v[134:137], v[174:177], v[42:45]
	v_mfma_f32_16x16x32_bf16 v[30:33], v[118:121], v[182:185], v[30:33]
	v_mfma_f32_16x16x32_bf16 v[26:29], v[134:137], v[182:185], v[26:29]
	v_mfma_f32_16x16x32_bf16 v[14:17], v[118:121], v[190:193], v[14:17]
	v_mfma_f32_16x16x32_bf16 v[10:13], v[134:137], v[190:193], v[10:13]
	s_setprio 0
	s_setprio 1
	v_mfma_f32_16x16x32_bf16 v[54:57], v[138:141], v[162:165], v[54:57]
	v_mfma_f32_16x16x32_bf16 v[50:53], v[146:149], v[162:165], v[50:53]
	v_mfma_f32_16x16x32_bf16 v[38:41], v[138:141], v[170:173], v[38:41]
	v_mfma_f32_16x16x32_bf16 v[34:37], v[146:149], v[170:173], v[34:37]
	v_mfma_f32_16x16x32_bf16 v[22:25], v[138:141], v[178:181], v[22:25]
	v_mfma_f32_16x16x32_bf16 v[18:21], v[146:149], v[178:181], v[18:21]
	v_mfma_f32_16x16x32_bf16 v[6:9], v[138:141], v[186:189], v[6:9]
	v_mfma_f32_16x16x32_bf16 v[2:5], v[146:149], v[186:189], v[2:5]
	v_mfma_f32_16x16x32_bf16 v[54:57], v[142:145], v[166:169], v[54:57]
	v_mfma_f32_16x16x32_bf16 v[50:53], v[150:153], v[166:169], v[50:53]
	v_mfma_f32_16x16x32_bf16 v[38:41], v[142:145], v[174:177], v[38:41]
	v_mfma_f32_16x16x32_bf16 v[34:37], v[150:153], v[174:177], v[34:37]
	v_mfma_f32_16x16x32_bf16 v[22:25], v[142:145], v[182:185], v[22:25]
	v_mfma_f32_16x16x32_bf16 v[18:21], v[150:153], v[182:185], v[18:21]
	v_mfma_f32_16x16x32_bf16 v[6:9], v[142:145], v[190:193], v[6:9]
	v_mfma_f32_16x16x32_bf16 v[2:5], v[150:153], v[190:193], v[2:5]
	s_setprio 0
	s_barrier
; #define PG8_STAGE(bufoff, gbase, voff) do { _Pragma("unroll") for (int _i = 0; _i < 2; ++_i) \
;         __builtin_amdgcn_global_load_lds((const unsigned*)((const char*)(gbase) + (voff)[_i]), (PG8_LAS unsigned*)(lds + (bufoff) + ldsw + _i * 8192), 16, 0, 0); } while (0)
; #define PG8_LDA(dst, b, h) do { _Pragma("unroll") for (int m = 0; m < 4; ++m) _Pragma("unroll") for (int k = 0; k < 2; ++k) dst[m][k] = *(const PG8_LAS bf16x8*)(lds + PG8_SA(b, h) + aoff + m * 2048 + k * 1024); } while (0)
; #define PG8_LDB(dst, b, h) do { _Pragma("unroll") for (int n = 0; n < 2; ++n) _Pragma("unroll") for (int k = 0; k < 2; ++k) dst[n][k] = *(const PG8_LAS bf16x8*)(lds + PG8_SB(b, h) + boff + n * 2048 + k * 1024); } while (0)
; #define PG8_MMA(ai, bj, At, Bt) do { __builtin_amdgcn_s_setprio(1); _Pragma("unroll") for (int m = 0; m < 4; ++m) _Pragma("unroll") for (int n = 0; n < 2; ++n) _Pragma("unroll") for (int k = 0; k < 2; ++k) \
;         acc[ai][bj][m][n] = __builtin_amdgcn_mfma_f32_16x16x32_bf16(Bt[n][k], At[m][k], acc[ai][bj][m][n], 0, 0, 0); __builtin_amdgcn_s_setprio(0); } while (0)
; #define PG8_WAIT_V(n) asm volatile("s_waitcnt vmcnt(" #n ")" ::: "memory")
; #define PG8_WAIT_L(n) asm volatile("s_waitcnt lgkmcnt(" #n ")" ::: "memory")
; #define PG8_BAR __builtin_amdgcn_s_barrier()
; #define PG8_SCHED __builtin_amdgcn_sched_barrier(0)
; template <class Epi, class Sched, bool ALIGN_EPI = false, bool SP2 = false>
; __device__ __forceinline__ void gemm_phase(PG8_LAS unsigned char* lds, const Gemm g, const Sched& S, const Epi& E, const int wave_id) {
;     ...
;             PG8_LDB(B0, 1, 0); PG8_LDB(B1, 1, 1); PG8_SCHED; PG8_LDA(At, 1, 0); PG8_STAGE(PG8_SA(0, 1), a2 + hstep, voffA);
;             PG8_WAIT_V(8); PG8_WAIT_L(0); PG8_BAR; PG8_MMA(0, 0, At, B0); PG8_MMA(0, 1, At, B1); PG8_BAR; PG8_SCHED;
	s_mov_b32 m0, s85
	s_nop 0
	global_load_lds_dwordx4 v208, s[88:89]
	s_add_i32 m0, s85, 0x2000
	s_nop 0
	global_load_lds_dwordx4 v212, s[88:89]
	s_add_i32 s85, 0, 0x18000
	s_add_i32 s88, 0, 0x1c000
	s_add_u32 s82, s82, 0x80000
	s_addc_u32 s83, s83, 0
	s_mov_b32 m0, s72
	s_nop 0
	global_load_lds_dwordx4 v206, s[82:83]
	ds_read_b128 v[114:117], v226 offset:32768
	ds_read_b128 v[118:121], v226 offset:33792
	ds_read_b128 v[130:133], v226 offset:34816
	ds_read_b128 v[134:137], v226 offset:35840
	ds_read_b128 v[138:141], v226 offset:49152
	ds_read_b128 v[142:145], v226 offset:50176
	ds_read_b128 v[146:149], v226 offset:51200
	ds_read_b128 v[150:153], v226 offset:52224
	s_mov_b32 m0, s73
	s_nop 0
	global_load_lds_dwordx4 v210, s[82:83]
	ds_read_b128 v[162:165], v244 offset:32768
	ds_read_b128 v[166:169], v244 offset:33792
	ds_read_b128 v[170:173], v244 offset:34816
	ds_read_b128 v[174:177], v244 offset:35840
	ds_read_b128 v[178:181], v244 offset:36864
	ds_read_b128 v[182:185], v244 offset:37888
	ds_read_b128 v[186:189], v244 offset:38912
	ds_read_b128 v[190:193], v244 offset:39936
	s_waitcnt vmcnt(8)
	s_waitcnt lgkmcnt(0)
	s_barrier
	s_setprio 1
	s_waitcnt lgkmcnt(0)
	v_mfma_f32_16x16x32_bf16 v[158:161], v[114:117], v[162:165], v[158:161]
	v_mfma_f32_16x16x32_bf16 v[154:157], v[130:133], v[162:165], v[154:157]
	v_mfma_f32_16x16x32_bf16 v[110:113], v[114:117], v[170:173], v[110:113]
	v_mfma_f32_16x16x32_bf16 v[106:109], v[130:133], v[170:173], v[106:109]
	v_mfma_f32_16x16x32_bf16 v[94:97], v[114:117], v[178:181], v[94:97]
	v_mfma_f32_16x16x32_bf16 v[90:93], v[130:133], v[178:181], v[90:93]
	v_mfma_f32_16x16x32_bf16 v[78:81], v[114:117], v[186:189], v[78:81]
	v_mfma_f32_16x16x32_bf16 v[74:77], v[130:133], v[186:189], v[74:77]
	v_mfma_f32_16x16x32_bf16 v[158:161], v[118:121], v[166:169], v[158:161]
	v_mfma_f32_16x16x32_bf16 v[154:157], v[134:137], v[166:169], v[154:157]
	v_mfma_f32_16x16x32_bf16 v[110:113], v[118:121], v[174:177], v[110:113]
	v_mfma_f32_16x16x32_bf16 v[106:109], v[134:137], v[174:177], v[106:109]
	v_mfma_f32_16x16x32_bf16 v[94:97], v[118:121], v[182:185], v[94:97]
	v_mfma_f32_16x16x32_bf16 v[90:93], v[134:137], v[182:185], v[90:93]
	v_mfma_f32_16x16x32_bf16 v[78:81], v[118:121], v[190:193], v[78:81]
	v_mfma_f32_16x16x32_bf16 v[74:77], v[134:137], v[190:193], v[74:77]
	s_setprio 0
	s_setprio 1
	v_mfma_f32_16x16x32_bf16 v[126:129], v[138:141], v[162:165], v[126:129]
	v_mfma_f32_16x16x32_bf16 v[122:125], v[146:149], v[162:165], v[122:125]
	v_mfma_f32_16x16x32_bf16 v[102:105], v[138:141], v[170:173], v[102:105]
	v_mfma_f32_16x16x32_bf16 v[98:101], v[146:149], v[170:173], v[98:101]
	v_mfma_f32_16x16x32_bf16 v[86:89], v[138:141], v[178:181], v[86:89]
	v_mfma_f32_16x16x32_bf16 v[82:85], v[146:149], v[178:181], v[82:85]
	v_mfma_f32_16x16x32_bf16 v[70:73], v[138:141], v[186:189], v[70:73]
	v_mfma_f32_16x16x32_bf16 v[66:69], v[146:149], v[186:189], v[66:69]
	v_mfma_f32_16x16x32_bf16 v[126:129], v[142:145], v[166:169], v[126:129]
	v_mfma_f32_16x16x32_bf16 v[122:125], v[150:153], v[166:169], v[122:125]
	v_mfma_f32_16x16x32_bf16 v[102:105], v[142:145], v[174:177], v[102:105]
	v_mfma_f32_16x16x32_bf16 v[98:101], v[150:153], v[174:177], v[98:101]
	v_mfma_f32_16x16x32_bf16 v[86:89], v[142:145], v[182:185], v[86:89]
	v_mfma_f32_16x16x32_bf16 v[82:85], v[150:153], v[182:185], v[82:85]
	v_mfma_f32_16x16x32_bf16 v[70:73], v[142:145], v[190:193], v[70:73]
	v_mfma_f32_16x16x32_bf16 v[66:69], v[150:153], v[190:193], v[66:69]
	s_setprio 0
	s_barrier
; #define PG8_STAGE(bufoff, gbase, voff) do { _Pragma("unroll") for (int _i = 0; _i < 2; ++_i) \
;         __builtin_amdgcn_global_load_lds((const unsigned*)((const char*)(gbase) + (voff)[_i]), (PG8_LAS unsigned*)(lds + (bufoff) + ldsw + _i * 8192), 16, 0, 0); } while (0)
; #define PG8_LDA(dst, b, h) do { _Pragma("unroll") for (int m = 0; m < 4; ++m) _Pragma("unroll") for (int k = 0; k < 2; ++k) dst[m][k] = *(const PG8_LAS bf16x8*)(lds + PG8_SA(b, h) + aoff + m * 2048 + k * 1024); } while (0)
; #define PG8_MMA(ai, bj, At, Bt) do { __builtin_amdgcn_s_setprio(1); _Pragma("unroll") for (int m = 0; m < 4; ++m) _Pragma("unroll") for (int n = 0; n < 2; ++n) _Pragma("unroll") for (int k = 0; k < 2; ++k) \
;         acc[ai][bj][m][n] = __builtin_amdgcn_mfma_f32_16x16x32_bf16(Bt[n][k], At[m][k], acc[ai][bj][m][n], 0, 0, 0); __builtin_amdgcn_s_setprio(0); } while (0)
; #define PG8_WAIT_V(n) asm volatile("s_waitcnt vmcnt(" #n ")" ::: "memory")
; #define PG8_WAIT_L(n) asm volatile("s_waitcnt lgkmcnt(" #n ")" ::: "memory")
; #define PG8_BAR __builtin_amdgcn_s_barrier()
; #define PG8_SCHED __builtin_amdgcn_sched_barrier(0)
; template <class Epi, class Sched, bool ALIGN_EPI = false, bool SP2 = false>
; __device__ __forceinline__ void gemm_phase(PG8_LAS unsigned char* lds, const Gemm g, const Sched& S, const Epi& E, const int wave_id) {
;     ...
;             PG8_LDA(At, 1, 1); PG8_STAGE(PG8_SB(1, 0), b3, voffB); PG8_STAGE(PG8_SB(1, 1), b3 + hstep, voffB); PG8_STAGE(PG8_SA(1, 0), a3, voffA);
;             PG8_WAIT_V(8); PG8_WAIT_L(0); PG8_BAR; PG8_MMA(1, 0, At, B0); PG8_MMA(1, 1, At, B1); PG8_BAR; PG8_SCHED;
	s_add_u32 vcc_lo, s82, 0xfff80080
	s_addc_u32 vcc_hi, s83, -1
	s_mov_b32 m0, s76
	s_nop 0
	global_load_lds_dwordx4 v206, vcc
	ds_read_b128 v[162:165], v244 offset:49152
	ds_read_b128 v[166:169], v244 offset:50176
	s_mov_b32 m0, s77
	s_add_i32 s82, s85, s69
	global_load_lds_dwordx4 v210, vcc
	ds_read_b128 v[170:173], v244 offset:51200
	ds_read_b128 v[174:177], v244 offset:52224
	s_add_u32 vcc_lo, s52, 0x80
	s_addc_u32 vcc_hi, s53, 0
	s_mov_b32 m0, s82
	s_nop 0
	global_load_lds_dwordx4 v208, vcc
	ds_read_b128 v[178:181], v244 offset:53248
	ds_read_b128 v[182:185], v244 offset:54272
	s_add_i32 m0, s82, 0x2000
	s_add_u32 s52, s52, 0x80080
	s_addc_u32 s53, s53, 0
	global_load_lds_dwordx4 v212, vcc
	ds_read_b128 v[186:189], v244 offset:55296
	ds_read_b128 v[190:193], v244 offset:56320
	s_add_i32 s82, s88, s69
	s_mov_b32 m0, s82
	s_nop 0
	global_load_lds_dwordx4 v208, s[52:53]
	s_add_i32 m0, s82, 0x2000
	s_nop 0
	global_load_lds_dwordx4 v212, s[52:53]
	s_waitcnt vmcnt(8)
	s_waitcnt lgkmcnt(0)
	s_barrier
	s_setprio 1
	s_waitcnt lgkmcnt(0)
	v_mfma_f32_16x16x32_bf16 v[62:65], v[114:117], v[162:165], v[62:65]
	v_mfma_f32_16x16x32_bf16 v[58:61], v[130:133], v[162:165], v[58:61]
	v_mfma_f32_16x16x32_bf16 v[46:49], v[114:117], v[170:173], v[46:49]
	v_mfma_f32_16x16x32_bf16 v[42:45], v[130:133], v[170:173], v[42:45]
	v_mfma_f32_16x16x32_bf16 v[30:33], v[114:117], v[178:181], v[30:33]
	v_mfma_f32_16x16x32_bf16 v[26:29], v[130:133], v[178:181], v[26:29]
	v_mfma_f32_16x16x32_bf16 v[14:17], v[114:117], v[186:189], v[14:17]
	v_mfma_f32_16x16x32_bf16 v[10:13], v[130:133], v[186:189], v[10:13]
	v_mfma_f32_16x16x32_bf16 v[62:65], v[118:121], v[166:169], v[62:65]
	v_mfma_f32_16x16x32_bf16 v[58:61], v[134:137], v[166:169], v[58:61]
	v_mfma_f32_16x16x32_bf16 v[46:49], v[118:121], v[174:177], v[46:49]
	v_mfma_f32_16x16x32_bf16 v[42:45], v[134:137], v[174:177], v[42:45]
	v_mfma_f32_16x16x32_bf16 v[30:33], v[118:121], v[182:185], v[30:33]
	v_mfma_f32_16x16x32_bf16 v[26:29], v[134:137], v[182:185], v[26:29]
	v_mfma_f32_16x16x32_bf16 v[14:17], v[118:121], v[190:193], v[14:17]
	v_mfma_f32_16x16x32_bf16 v[10:13], v[134:137], v[190:193], v[10:13]
	s_setprio 0
	s_setprio 1
	v_mfma_f32_16x16x32_bf16 v[54:57], v[138:141], v[162:165], v[54:57]
	v_mfma_f32_16x16x32_bf16 v[50:53], v[146:149], v[162:165], v[50:53]
	v_mfma_f32_16x16x32_bf16 v[38:41], v[138:141], v[170:173], v[38:41]
	v_mfma_f32_16x16x32_bf16 v[34:37], v[146:149], v[170:173], v[34:37]
	v_mfma_f32_16x16x32_bf16 v[22:25], v[138:141], v[178:181], v[22:25]
	v_mfma_f32_16x16x32_bf16 v[18:21], v[146:149], v[178:181], v[18:21]
	v_mfma_f32_16x16x32_bf16 v[6:9], v[138:141], v[186:189], v[6:9]
	v_mfma_f32_16x16x32_bf16 v[2:5], v[146:149], v[186:189], v[2:5]
	v_mfma_f32_16x16x32_bf16 v[54:57], v[142:145], v[166:169], v[54:57]
	v_mfma_f32_16x16x32_bf16 v[50:53], v[150:153], v[166:169], v[50:53]
	v_mfma_f32_16x16x32_bf16 v[38:41], v[142:145], v[174:177], v[38:41]
	v_mfma_f32_16x16x32_bf16 v[34:37], v[150:153], v[174:177], v[34:37]
	v_mfma_f32_16x16x32_bf16 v[22:25], v[142:145], v[182:185], v[22:25]
	v_mfma_f32_16x16x32_bf16 v[18:21], v[150:153], v[182:185], v[18:21]
	v_mfma_f32_16x16x32_bf16 v[6:9], v[142:145], v[190:193], v[6:9]
	v_mfma_f32_16x16x32_bf16 v[2:5], v[150:153], v[190:193], v[2:5]
	s_setprio 0
	s_barrier
	s_add_i32 s84, s84, 2
	s_add_u32 s46, s46, 0x100
	s_addc_u32 s47, s47, 0
	s_add_u32 s80, s80, 0x100
	s_addc_u32 s81, s81, 0
	s_cmp_gt_u32 s84, 29
	s_cbranch_scc0 .LBB0_904
	s_and_b64 vcc, exec, s[16:17]
	s_mov_b32 s50, 0x90000
	s_mov_b32 s51, 0xa0000
	s_mov_b32 s82, 0xb0000
	s_cbranch_vccz .LBB0_907
	s_barrier
